# variant of previous: merged M-phase run ordered (block,n),m,k so each weight-fragment pair is held for 8 consecutive MFMAs
# speedup vs baseline: 1.0100x; 1.0012x over previous
.LBB0_1790:
	ds_read_b128 v[146:149], v159
	ds_read_b128 v[150:153], v159 offset:1024
	ds_read_b128 v[164:167], v159 offset:2048
	ds_read_b128 v[168:171], v159 offset:3072
	ds_read_b128 v[172:175], v160
	ds_read_b128 v[176:179], v160 offset:1024
	ds_read_b128 v[186:189], v160 offset:2048
	ds_read_b128 v[190:193], v160 offset:3072
	s_add_u32 s79, s6, 0xfff00080
	s_addc_u32 s80, s7, -1
	s_cmp_eq_u32 s78, 60
	s_cselect_b32 s91, s45, s80
	s_cselect_b32 s90, s74, s79
	s_cselect_b32 s89, s43, s77
	s_cselect_b32 s88, s75, s76
	s_add_i32 m0, s33, 0xc000
	ds_read_b128 v[194:197], v161
	ds_read_b128 v[198:201], v161 offset:1024
	ds_read_b128 v[202:205], v161 offset:2048
	ds_read_b128 v[206:209], v161 offset:3072
	ds_read_b128 v[210:213], v161 offset:4096
	ds_read_b128 v[214:217], v161 offset:5120
	ds_read_b128 v[218:221], v161 offset:6144
	ds_read_b128 v[222:225], v161 offset:7168
	global_load_lds_dwordx4 v138, s[6:7]
	s_add_i32 m0, s33, 0xe000
	s_nop 0
	global_load_lds_dwordx4 v140, s[6:7]
	s_waitcnt vmcnt(8)
	s_waitcnt lgkmcnt(0)
	s_barrier
	s_setprio 1
	v_mfma_f32_16x16x32_bf16 v[126:129], v[146:149], v[194:197], v[126:129]
	v_mfma_f32_16x16x32_bf16 v[126:129], v[150:153], v[198:201], v[126:129]
	v_mfma_f32_16x16x32_bf16 v[114:117], v[146:149], v[202:205], v[114:117]
	v_mfma_f32_16x16x32_bf16 v[114:117], v[150:153], v[206:209], v[114:117]
	v_mfma_f32_16x16x32_bf16 v[98:101], v[146:149], v[210:213], v[98:101]
	v_mfma_f32_16x16x32_bf16 v[98:101], v[150:153], v[214:217], v[98:101]
	v_mfma_f32_16x16x32_bf16 v[82:85], v[146:149], v[218:221], v[82:85]
	v_mfma_f32_16x16x32_bf16 v[82:85], v[150:153], v[222:225], v[82:85]
	v_mfma_f32_16x16x32_bf16 v[122:125], v[164:167], v[194:197], v[122:125]
	v_mfma_f32_16x16x32_bf16 v[122:125], v[168:171], v[198:201], v[122:125]
	v_mfma_f32_16x16x32_bf16 v[106:109], v[164:167], v[202:205], v[106:109]
	v_mfma_f32_16x16x32_bf16 v[106:109], v[168:171], v[206:209], v[106:109]
	v_mfma_f32_16x16x32_bf16 v[90:93], v[164:167], v[210:213], v[90:93]
	v_mfma_f32_16x16x32_bf16 v[90:93], v[168:171], v[214:217], v[90:93]
	v_mfma_f32_16x16x32_bf16 v[74:77], v[164:167], v[218:221], v[74:77]
	v_mfma_f32_16x16x32_bf16 v[74:77], v[168:171], v[222:225], v[74:77]
	v_mfma_f32_16x16x32_bf16 v[118:121], v[172:175], v[194:197], v[118:121]
	v_mfma_f32_16x16x32_bf16 v[118:121], v[176:179], v[198:201], v[118:121]
	v_mfma_f32_16x16x32_bf16 v[102:105], v[172:175], v[202:205], v[102:105]
	v_mfma_f32_16x16x32_bf16 v[102:105], v[176:179], v[206:209], v[102:105]
	v_mfma_f32_16x16x32_bf16 v[86:89], v[172:175], v[210:213], v[86:89]
	v_mfma_f32_16x16x32_bf16 v[86:89], v[176:179], v[214:217], v[86:89]
	v_mfma_f32_16x16x32_bf16 v[70:73], v[172:175], v[218:221], v[70:73]
	v_mfma_f32_16x16x32_bf16 v[70:73], v[176:179], v[222:225], v[70:73]
	v_mfma_f32_16x16x32_bf16 v[110:113], v[186:189], v[194:197], v[110:113]
	v_mfma_f32_16x16x32_bf16 v[110:113], v[190:193], v[198:201], v[110:113]
	v_mfma_f32_16x16x32_bf16 v[94:97], v[186:189], v[202:205], v[94:97]
	v_mfma_f32_16x16x32_bf16 v[94:97], v[190:193], v[206:209], v[94:97]
	v_mfma_f32_16x16x32_bf16 v[78:81], v[186:189], v[210:213], v[78:81]
	v_mfma_f32_16x16x32_bf16 v[78:81], v[190:193], v[214:217], v[78:81]
	v_mfma_f32_16x16x32_bf16 v[66:69], v[186:189], v[218:221], v[66:69]
	v_mfma_f32_16x16x32_bf16 v[66:69], v[190:193], v[222:225], v[66:69]
	s_setprio 0
	s_barrier
	s_add_i32 s79, s69, s25
	s_add_u32 s98, s88, 0x80
	s_addc_u32 s99, s89, 0
	s_mov_b32 m0, s79
	ds_read_b128 v[194:197], v161 offset:16384
	ds_read_b128 v[198:201], v161 offset:17408
	ds_read_b128 v[202:205], v161 offset:18432
	ds_read_b128 v[206:209], v161 offset:19456
	ds_read_b128 v[210:213], v161 offset:20480
	ds_read_b128 v[214:217], v161 offset:21504
	ds_read_b128 v[218:221], v161 offset:22528
	ds_read_b128 v[222:225], v161 offset:23552
	global_load_lds_dwordx4 v132, s[88:89]
	s_add_i32 m0, s79, 0x2000
	s_add_u32 s80, s88, 0x100000
	s_addc_u32 s81, s89, 0
	s_add_i32 s79, s70, s25
	global_load_lds_dwordx4 v136, s[88:89]
	s_mov_b32 m0, s79
	global_load_lds_dwordx4 v132, s[80:81]
	s_add_i32 m0, s79, 0x2000
	s_nop 0
	global_load_lds_dwordx4 v136, s[80:81]
	s_add_u32 s100, s90, 0x80
	s_addc_u32 s101, s91, 0
	s_mov_b32 m0, s33
	s_nop 0
	global_load_lds_dwordx4 v130, s[90:91]
	s_mov_b32 m0, s35
	s_nop 0
	global_load_lds_dwordx4 v134, s[90:91]
	s_waitcnt vmcnt(8)
	s_waitcnt lgkmcnt(0)
	s_barrier
	s_setprio 1
	v_mfma_f32_16x16x32_bf16 v[62:65], v[146:149], v[194:197], v[62:65]
	v_mfma_f32_16x16x32_bf16 v[62:65], v[150:153], v[198:201], v[62:65]
	v_mfma_f32_16x16x32_bf16 v[50:53], v[146:149], v[202:205], v[50:53]
	v_mfma_f32_16x16x32_bf16 v[50:53], v[150:153], v[206:209], v[50:53]
	v_mfma_f32_16x16x32_bf16 v[34:37], v[146:149], v[210:213], v[34:37]
	v_mfma_f32_16x16x32_bf16 v[34:37], v[150:153], v[214:217], v[34:37]
	v_mfma_f32_16x16x32_bf16 v[18:21], v[146:149], v[218:221], v[18:21]
	v_mfma_f32_16x16x32_bf16 v[18:21], v[150:153], v[222:225], v[18:21]
	v_mfma_f32_16x16x32_bf16 v[58:61], v[164:167], v[194:197], v[58:61]
	v_mfma_f32_16x16x32_bf16 v[58:61], v[168:171], v[198:201], v[58:61]
	v_mfma_f32_16x16x32_bf16 v[42:45], v[164:167], v[202:205], v[42:45]
	v_mfma_f32_16x16x32_bf16 v[42:45], v[168:171], v[206:209], v[42:45]
	v_mfma_f32_16x16x32_bf16 v[26:29], v[164:167], v[210:213], v[26:29]
	v_mfma_f32_16x16x32_bf16 v[26:29], v[168:171], v[214:217], v[26:29]
	v_mfma_f32_16x16x32_bf16 v[10:13], v[164:167], v[218:221], v[10:13]
	v_mfma_f32_16x16x32_bf16 v[10:13], v[168:171], v[222:225], v[10:13]
	v_mfma_f32_16x16x32_bf16 v[54:57], v[172:175], v[194:197], v[54:57]
	v_mfma_f32_16x16x32_bf16 v[54:57], v[176:179], v[198:201], v[54:57]
	v_mfma_f32_16x16x32_bf16 v[38:41], v[172:175], v[202:205], v[38:41]
	v_mfma_f32_16x16x32_bf16 v[38:41], v[176:179], v[206:209], v[38:41]
	v_mfma_f32_16x16x32_bf16 v[22:25], v[172:175], v[210:213], v[22:25]
	v_mfma_f32_16x16x32_bf16 v[22:25], v[176:179], v[214:217], v[22:25]
	v_mfma_f32_16x16x32_bf16 v[6:9], v[172:175], v[218:221], v[6:9]
	v_mfma_f32_16x16x32_bf16 v[6:9], v[176:179], v[222:225], v[6:9]
	v_mfma_f32_16x16x32_bf16 v[46:49], v[186:189], v[194:197], v[46:49]
	v_mfma_f32_16x16x32_bf16 v[46:49], v[190:193], v[198:201], v[46:49]
	v_mfma_f32_16x16x32_bf16 v[30:33], v[186:189], v[202:205], v[30:33]
	v_mfma_f32_16x16x32_bf16 v[30:33], v[190:193], v[206:209], v[30:33]
	v_mfma_f32_16x16x32_bf16 v[14:17], v[186:189], v[210:213], v[14:17]
	v_mfma_f32_16x16x32_bf16 v[14:17], v[190:193], v[214:217], v[14:17]
	v_mfma_f32_16x16x32_bf16 v[2:5], v[186:189], v[218:221], v[2:5]
	v_mfma_f32_16x16x32_bf16 v[2:5], v[190:193], v[222:225], v[2:5]
	s_setprio 0
	s_barrier
	s_add_i32 s79, 0, 0x18000
	s_add_i32 s82, 0, 0x1c000
	v_add_u32_e32 v168, s79, v155
	v_add_u32_e32 v183, s82, v155
	ds_read_b128 v[146:149], v168
	ds_read_b128 v[150:153], v168 offset:1024
	ds_read_b128 v[164:167], v168 offset:2048
	ds_read_b128 v[168:171], v168 offset:3072
	ds_read_b128 v[172:175], v183
	ds_read_b128 v[176:179], v183 offset:1024
	ds_read_b128 v[186:189], v183 offset:2048
	ds_read_b128 v[190:193], v183 offset:3072
	s_add_u32 s80, s90, 0x100000
	s_addc_u32 s81, s91, 0
	s_mov_b32 m0, s59
	ds_read_b128 v[194:197], v161 offset:32768
	ds_read_b128 v[198:201], v161 offset:33792
	ds_read_b128 v[202:205], v161 offset:34816
	ds_read_b128 v[206:209], v161 offset:35840
	ds_read_b128 v[210:213], v161 offset:36864
	ds_read_b128 v[214:217], v161 offset:37888
	ds_read_b128 v[218:221], v161 offset:38912
	ds_read_b128 v[222:225], v161 offset:39936
	global_load_lds_dwordx4 v130, s[80:81]
	s_mov_b32 m0, s62
	s_nop 0
	global_load_lds_dwordx4 v134, s[80:81]
	s_waitcnt vmcnt(8)
	s_waitcnt lgkmcnt(0)
	s_barrier
	s_setprio 1
	v_mfma_f32_16x16x32_bf16 v[126:129], v[146:149], v[194:197], v[126:129]
	v_mfma_f32_16x16x32_bf16 v[126:129], v[150:153], v[198:201], v[126:129]
	v_mfma_f32_16x16x32_bf16 v[114:117], v[146:149], v[202:205], v[114:117]
	v_mfma_f32_16x16x32_bf16 v[114:117], v[150:153], v[206:209], v[114:117]
	v_mfma_f32_16x16x32_bf16 v[98:101], v[146:149], v[210:213], v[98:101]
	v_mfma_f32_16x16x32_bf16 v[98:101], v[150:153], v[214:217], v[98:101]
	v_mfma_f32_16x16x32_bf16 v[82:85], v[146:149], v[218:221], v[82:85]
	v_mfma_f32_16x16x32_bf16 v[82:85], v[150:153], v[222:225], v[82:85]
	v_mfma_f32_16x16x32_bf16 v[122:125], v[164:167], v[194:197], v[122:125]
	v_mfma_f32_16x16x32_bf16 v[122:125], v[168:171], v[198:201], v[122:125]
	v_mfma_f32_16x16x32_bf16 v[106:109], v[164:167], v[202:205], v[106:109]
	v_mfma_f32_16x16x32_bf16 v[106:109], v[168:171], v[206:209], v[106:109]
	v_mfma_f32_16x16x32_bf16 v[90:93], v[164:167], v[210:213], v[90:93]
	v_mfma_f32_16x16x32_bf16 v[90:93], v[168:171], v[214:217], v[90:93]
	v_mfma_f32_16x16x32_bf16 v[74:77], v[164:167], v[218:221], v[74:77]
	v_mfma_f32_16x16x32_bf16 v[74:77], v[168:171], v[222:225], v[74:77]
	v_mfma_f32_16x16x32_bf16 v[118:121], v[172:175], v[194:197], v[118:121]
	v_mfma_f32_16x16x32_bf16 v[118:121], v[176:179], v[198:201], v[118:121]
	v_mfma_f32_16x16x32_bf16 v[102:105], v[172:175], v[202:205], v[102:105]
	v_mfma_f32_16x16x32_bf16 v[102:105], v[176:179], v[206:209], v[102:105]
	v_mfma_f32_16x16x32_bf16 v[86:89], v[172:175], v[210:213], v[86:89]
	v_mfma_f32_16x16x32_bf16 v[86:89], v[176:179], v[214:217], v[86:89]
	v_mfma_f32_16x16x32_bf16 v[70:73], v[172:175], v[218:221], v[70:73]
	v_mfma_f32_16x16x32_bf16 v[70:73], v[176:179], v[222:225], v[70:73]
	v_mfma_f32_16x16x32_bf16 v[110:113], v[186:189], v[194:197], v[110:113]
	v_mfma_f32_16x16x32_bf16 v[110:113], v[190:193], v[198:201], v[110:113]
	v_mfma_f32_16x16x32_bf16 v[94:97], v[186:189], v[202:205], v[94:97]
	v_mfma_f32_16x16x32_bf16 v[94:97], v[190:193], v[206:209], v[94:97]
	v_mfma_f32_16x16x32_bf16 v[78:81], v[186:189], v[210:213], v[78:81]
	v_mfma_f32_16x16x32_bf16 v[78:81], v[190:193], v[214:217], v[78:81]
	v_mfma_f32_16x16x32_bf16 v[66:69], v[186:189], v[218:221], v[66:69]
	v_mfma_f32_16x16x32_bf16 v[66:69], v[190:193], v[222:225], v[66:69]
	s_setprio 0
	s_barrier
	s_add_i32 s79, s79, s25
	s_mov_b32 m0, s79
	ds_read_b128 v[194:197], v161 offset:49152
	ds_read_b128 v[198:201], v161 offset:50176
	ds_read_b128 v[202:205], v161 offset:51200
	ds_read_b128 v[206:209], v161 offset:52224
	ds_read_b128 v[210:213], v161 offset:53248
	ds_read_b128 v[214:217], v161 offset:54272
	ds_read_b128 v[218:221], v161 offset:55296
	ds_read_b128 v[222:225], v161 offset:56320
	global_load_lds_dwordx4 v132, s[98:99]
	s_add_i32 m0, s79, 0x2000
	s_add_u32 s80, s88, 0x100080
	s_addc_u32 s81, s89, 0
	s_add_i32 s79, s82, s25
	global_load_lds_dwordx4 v136, s[98:99]
	s_mov_b32 m0, s79
	s_nop 0
	global_load_lds_dwordx4 v132, s[80:81]
	s_add_i32 m0, s79, 0x2000
	s_nop 0
	global_load_lds_dwordx4 v136, s[80:81]
	s_mov_b32 m0, s66
	s_nop 0
	global_load_lds_dwordx4 v130, s[100:101]
	s_mov_b32 m0, s67
	s_nop 0
	global_load_lds_dwordx4 v134, s[100:101]
	s_waitcnt vmcnt(8)
	s_waitcnt lgkmcnt(0)
	s_barrier
	s_setprio 1
	v_mfma_f32_16x16x32_bf16 v[62:65], v[146:149], v[194:197], v[62:65]
	v_mfma_f32_16x16x32_bf16 v[62:65], v[150:153], v[198:201], v[62:65]
	v_mfma_f32_16x16x32_bf16 v[50:53], v[146:149], v[202:205], v[50:53]
	v_mfma_f32_16x16x32_bf16 v[50:53], v[150:153], v[206:209], v[50:53]
	v_mfma_f32_16x16x32_bf16 v[34:37], v[146:149], v[210:213], v[34:37]
	v_mfma_f32_16x16x32_bf16 v[34:37], v[150:153], v[214:217], v[34:37]
	v_mfma_f32_16x16x32_bf16 v[18:21], v[146:149], v[218:221], v[18:21]
	v_mfma_f32_16x16x32_bf16 v[18:21], v[150:153], v[222:225], v[18:21]
	v_mfma_f32_16x16x32_bf16 v[58:61], v[164:167], v[194:197], v[58:61]
	v_mfma_f32_16x16x32_bf16 v[58:61], v[168:171], v[198:201], v[58:61]
	v_mfma_f32_16x16x32_bf16 v[42:45], v[164:167], v[202:205], v[42:45]
	v_mfma_f32_16x16x32_bf16 v[42:45], v[168:171], v[206:209], v[42:45]
	v_mfma_f32_16x16x32_bf16 v[26:29], v[164:167], v[210:213], v[26:29]
	v_mfma_f32_16x16x32_bf16 v[26:29], v[168:171], v[214:217], v[26:29]
	v_mfma_f32_16x16x32_bf16 v[10:13], v[164:167], v[218:221], v[10:13]
	v_mfma_f32_16x16x32_bf16 v[10:13], v[168:171], v[222:225], v[10:13]
	v_mfma_f32_16x16x32_bf16 v[54:57], v[172:175], v[194:197], v[54:57]
	v_mfma_f32_16x16x32_bf16 v[54:57], v[176:179], v[198:201], v[54:57]
	v_mfma_f32_16x16x32_bf16 v[38:41], v[172:175], v[202:205], v[38:41]
	v_mfma_f32_16x16x32_bf16 v[38:41], v[176:179], v[206:209], v[38:41]
	v_mfma_f32_16x16x32_bf16 v[22:25], v[172:175], v[210:213], v[22:25]
	v_mfma_f32_16x16x32_bf16 v[22:25], v[176:179], v[214:217], v[22:25]
	v_mfma_f32_16x16x32_bf16 v[6:9], v[172:175], v[218:221], v[6:9]
	v_mfma_f32_16x16x32_bf16 v[6:9], v[176:179], v[222:225], v[6:9]
	v_mfma_f32_16x16x32_bf16 v[46:49], v[186:189], v[194:197], v[46:49]
	v_mfma_f32_16x16x32_bf16 v[46:49], v[190:193], v[198:201], v[46:49]
	v_mfma_f32_16x16x32_bf16 v[30:33], v[186:189], v[202:205], v[30:33]
	v_mfma_f32_16x16x32_bf16 v[30:33], v[190:193], v[206:209], v[30:33]
	v_mfma_f32_16x16x32_bf16 v[14:17], v[186:189], v[210:213], v[14:17]
	v_mfma_f32_16x16x32_bf16 v[14:17], v[190:193], v[214:217], v[14:17]
	v_mfma_f32_16x16x32_bf16 v[2:5], v[186:189], v[218:221], v[2:5]
	v_mfma_f32_16x16x32_bf16 v[2:5], v[190:193], v[222:225], v[2:5]
	s_setprio 0
	s_barrier
	s_add_i32 s78, s78, 2
	s_add_u32 s6, s6, 0x100
	s_addc_u32 s7, s7, 0
	s_add_u32 s76, s76, 0x100
	s_addc_u32 s77, s77, 0
	s_cmp_gt_u32 s78, 61
	s_cbranch_scc0 .LBB0_1790
	s_and_b64 vcc, exec, s[40:41]
	s_cbranch_vccz .LBB0_1793
	s_barrier

.LBB0_2109:
	ds_read_b128 v[130:133], v155
	ds_read_b128 v[134:137], v155 offset:1024
	ds_read_b128 v[138:141], v155 offset:2048
	ds_read_b128 v[142:145], v155 offset:3072
	ds_read_b128 v[166:169], v176
	ds_read_b128 v[170:173], v176 offset:1024
	ds_read_b128 v[186:189], v176 offset:2048
	ds_read_b128 v[190:193], v176 offset:3072
	s_add_u32 s74, s50, 0xfff00080
	s_addc_u32 s75, s51, -1
	s_cmp_eq_u32 s73, 60
	s_cselect_b32 s85, s26, s75
	s_cselect_b32 s84, s45, s74
	s_cselect_b32 s83, s43, s72
	s_cselect_b32 s82, s70, s71
	s_add_i32 m0, s23, 0xc000
	ds_read_b128 v[194:197], v177
	ds_read_b128 v[198:201], v177 offset:1024
	ds_read_b128 v[202:205], v177 offset:2048
	ds_read_b128 v[206:209], v177 offset:3072
	ds_read_b128 v[210:213], v177 offset:4096
	ds_read_b128 v[214:217], v177 offset:5120
	ds_read_b128 v[218:221], v177 offset:6144
	ds_read_b128 v[222:225], v177 offset:7168
	global_load_lds_dwordx4 v158, s[50:51]
	s_add_i32 m0, s23, 0xe000
	s_nop 0
	global_load_lds_dwordx4 v160, s[50:51]
	s_waitcnt vmcnt(8)
	s_waitcnt lgkmcnt(0)
	s_barrier
	s_setprio 1
	v_mfma_f32_16x16x32_bf16 v[126:129], v[130:133], v[194:197], v[126:129]
	v_mfma_f32_16x16x32_bf16 v[126:129], v[134:137], v[198:201], v[126:129]
	v_mfma_f32_16x16x32_bf16 v[110:113], v[130:133], v[202:205], v[110:113]
	v_mfma_f32_16x16x32_bf16 v[110:113], v[134:137], v[206:209], v[110:113]
	v_mfma_f32_16x16x32_bf16 v[94:97], v[130:133], v[210:213], v[94:97]
	v_mfma_f32_16x16x32_bf16 v[94:97], v[134:137], v[214:217], v[94:97]
	v_mfma_f32_16x16x32_bf16 v[78:81], v[130:133], v[218:221], v[78:81]
	v_mfma_f32_16x16x32_bf16 v[78:81], v[134:137], v[222:225], v[78:81]
	v_mfma_f32_16x16x32_bf16 v[122:125], v[138:141], v[194:197], v[122:125]
	v_mfma_f32_16x16x32_bf16 v[122:125], v[142:145], v[198:201], v[122:125]
	v_mfma_f32_16x16x32_bf16 v[106:109], v[138:141], v[202:205], v[106:109]
	v_mfma_f32_16x16x32_bf16 v[106:109], v[142:145], v[206:209], v[106:109]
	v_mfma_f32_16x16x32_bf16 v[90:93], v[138:141], v[210:213], v[90:93]
	v_mfma_f32_16x16x32_bf16 v[90:93], v[142:145], v[214:217], v[90:93]
	v_mfma_f32_16x16x32_bf16 v[74:77], v[138:141], v[218:221], v[74:77]
	v_mfma_f32_16x16x32_bf16 v[74:77], v[142:145], v[222:225], v[74:77]
	v_mfma_f32_16x16x32_bf16 v[118:121], v[166:169], v[194:197], v[118:121]
	v_mfma_f32_16x16x32_bf16 v[118:121], v[170:173], v[198:201], v[118:121]
	v_mfma_f32_16x16x32_bf16 v[102:105], v[166:169], v[202:205], v[102:105]
	v_mfma_f32_16x16x32_bf16 v[102:105], v[170:173], v[206:209], v[102:105]
	v_mfma_f32_16x16x32_bf16 v[86:89], v[166:169], v[210:213], v[86:89]
	v_mfma_f32_16x16x32_bf16 v[86:89], v[170:173], v[214:217], v[86:89]
	v_mfma_f32_16x16x32_bf16 v[70:73], v[166:169], v[218:221], v[70:73]
	v_mfma_f32_16x16x32_bf16 v[70:73], v[170:173], v[222:225], v[70:73]
	v_mfma_f32_16x16x32_bf16 v[114:117], v[186:189], v[194:197], v[114:117]
	v_mfma_f32_16x16x32_bf16 v[114:117], v[190:193], v[198:201], v[114:117]
	v_mfma_f32_16x16x32_bf16 v[98:101], v[186:189], v[202:205], v[98:101]
	v_mfma_f32_16x16x32_bf16 v[98:101], v[190:193], v[206:209], v[98:101]
	v_mfma_f32_16x16x32_bf16 v[82:85], v[186:189], v[210:213], v[82:85]
	v_mfma_f32_16x16x32_bf16 v[82:85], v[190:193], v[214:217], v[82:85]
	v_mfma_f32_16x16x32_bf16 v[66:69], v[186:189], v[218:221], v[66:69]
	v_mfma_f32_16x16x32_bf16 v[66:69], v[190:193], v[222:225], v[66:69]
	s_setprio 0
	s_barrier
	s_add_i32 s74, s67, s3
	s_add_u32 s98, s82, 0x80
	s_addc_u32 s99, s83, 0
	s_mov_b32 m0, s74
	ds_read_b128 v[194:197], v177 offset:16384
	ds_read_b128 v[198:201], v177 offset:17408
	ds_read_b128 v[202:205], v177 offset:18432
	ds_read_b128 v[206:209], v177 offset:19456
	ds_read_b128 v[210:213], v177 offset:20480
	ds_read_b128 v[214:217], v177 offset:21504
	ds_read_b128 v[218:221], v177 offset:22528
	ds_read_b128 v[222:225], v177 offset:23552
	global_load_lds_dwordx4 v148, s[82:83]
	s_add_i32 m0, s74, 0x2000
	s_add_u32 s74, s82, 0x100000
	s_addc_u32 s75, s83, 0
	s_add_i32 s76, s68, s3
	global_load_lds_dwordx4 v152, s[82:83]
	s_mov_b32 m0, s76
	global_load_lds_dwordx4 v148, s[74:75]
	s_add_i32 m0, s76, 0x2000
	s_nop 0
	global_load_lds_dwordx4 v152, s[74:75]
	s_add_u32 s100, s84, 0x80
	s_addc_u32 s101, s85, 0
	s_mov_b32 m0, s23
	s_nop 0
	global_load_lds_dwordx4 v146, s[84:85]
	s_mov_b32 m0, s25
	s_nop 0
	global_load_lds_dwordx4 v150, s[84:85]
	s_waitcnt vmcnt(8)
	s_waitcnt lgkmcnt(0)
	s_barrier
	s_setprio 1
	v_mfma_f32_16x16x32_bf16 v[62:65], v[130:133], v[194:197], v[62:65]
	v_mfma_f32_16x16x32_bf16 v[62:65], v[134:137], v[198:201], v[62:65]
	v_mfma_f32_16x16x32_bf16 v[46:49], v[130:133], v[202:205], v[46:49]
	v_mfma_f32_16x16x32_bf16 v[46:49], v[134:137], v[206:209], v[46:49]
	v_mfma_f32_16x16x32_bf16 v[30:33], v[130:133], v[210:213], v[30:33]
	v_mfma_f32_16x16x32_bf16 v[30:33], v[134:137], v[214:217], v[30:33]
	v_mfma_f32_16x16x32_bf16 v[14:17], v[130:133], v[218:221], v[14:17]
	v_mfma_f32_16x16x32_bf16 v[14:17], v[134:137], v[222:225], v[14:17]
	v_mfma_f32_16x16x32_bf16 v[58:61], v[138:141], v[194:197], v[58:61]
	v_mfma_f32_16x16x32_bf16 v[58:61], v[142:145], v[198:201], v[58:61]
	v_mfma_f32_16x16x32_bf16 v[42:45], v[138:141], v[202:205], v[42:45]
	v_mfma_f32_16x16x32_bf16 v[42:45], v[142:145], v[206:209], v[42:45]
	v_mfma_f32_16x16x32_bf16 v[26:29], v[138:141], v[210:213], v[26:29]
	v_mfma_f32_16x16x32_bf16 v[26:29], v[142:145], v[214:217], v[26:29]
	v_mfma_f32_16x16x32_bf16 v[10:13], v[138:141], v[218:221], v[10:13]
	v_mfma_f32_16x16x32_bf16 v[10:13], v[142:145], v[222:225], v[10:13]
	v_mfma_f32_16x16x32_bf16 v[54:57], v[166:169], v[194:197], v[54:57]
	v_mfma_f32_16x16x32_bf16 v[54:57], v[170:173], v[198:201], v[54:57]
	v_mfma_f32_16x16x32_bf16 v[38:41], v[166:169], v[202:205], v[38:41]
	v_mfma_f32_16x16x32_bf16 v[38:41], v[170:173], v[206:209], v[38:41]
	v_mfma_f32_16x16x32_bf16 v[22:25], v[166:169], v[210:213], v[22:25]
	v_mfma_f32_16x16x32_bf16 v[22:25], v[170:173], v[214:217], v[22:25]
	v_mfma_f32_16x16x32_bf16 v[6:9], v[166:169], v[218:221], v[6:9]
	v_mfma_f32_16x16x32_bf16 v[6:9], v[170:173], v[222:225], v[6:9]
	v_mfma_f32_16x16x32_bf16 v[50:53], v[186:189], v[194:197], v[50:53]
	v_mfma_f32_16x16x32_bf16 v[50:53], v[190:193], v[198:201], v[50:53]
	v_mfma_f32_16x16x32_bf16 v[34:37], v[186:189], v[202:205], v[34:37]
	v_mfma_f32_16x16x32_bf16 v[34:37], v[190:193], v[206:209], v[34:37]
	v_mfma_f32_16x16x32_bf16 v[18:21], v[186:189], v[210:213], v[18:21]
	v_mfma_f32_16x16x32_bf16 v[18:21], v[190:193], v[214:217], v[18:21]
	v_mfma_f32_16x16x32_bf16 v[2:5], v[186:189], v[218:221], v[2:5]
	v_mfma_f32_16x16x32_bf16 v[2:5], v[190:193], v[222:225], v[2:5]
	s_setprio 0
	s_barrier
	s_add_i32 s76, 0, 0x18000
	s_add_i32 s77, 0, 0x1c000
	v_add_u32_e32 v142, s76, v174
	v_add_u32_e32 v179, s77, v174
	ds_read_b128 v[130:133], v142
	ds_read_b128 v[134:137], v142 offset:1024
	ds_read_b128 v[138:141], v142 offset:2048
	ds_read_b128 v[142:145], v142 offset:3072
	ds_read_b128 v[166:169], v179
	ds_read_b128 v[170:173], v179 offset:1024
	ds_read_b128 v[186:189], v179 offset:2048
	ds_read_b128 v[190:193], v179 offset:3072
	s_add_u32 s74, s84, 0x100000
	s_addc_u32 s75, s85, 0
	s_mov_b32 m0, s33
	ds_read_b128 v[194:197], v177 offset:32768
	ds_read_b128 v[198:201], v177 offset:33792
	ds_read_b128 v[202:205], v177 offset:34816
	ds_read_b128 v[206:209], v177 offset:35840
	ds_read_b128 v[210:213], v177 offset:36864
	ds_read_b128 v[214:217], v177 offset:37888
	ds_read_b128 v[218:221], v177 offset:38912
	ds_read_b128 v[222:225], v177 offset:39936
	global_load_lds_dwordx4 v146, s[74:75]
	s_mov_b32 m0, s35
	s_nop 0
	global_load_lds_dwordx4 v150, s[74:75]
	s_waitcnt vmcnt(8)
	s_waitcnt lgkmcnt(0)
	s_barrier
	s_setprio 1
	v_mfma_f32_16x16x32_bf16 v[126:129], v[130:133], v[194:197], v[126:129]
	v_mfma_f32_16x16x32_bf16 v[126:129], v[134:137], v[198:201], v[126:129]
	v_mfma_f32_16x16x32_bf16 v[110:113], v[130:133], v[202:205], v[110:113]
	v_mfma_f32_16x16x32_bf16 v[110:113], v[134:137], v[206:209], v[110:113]
	v_mfma_f32_16x16x32_bf16 v[94:97], v[130:133], v[210:213], v[94:97]
	v_mfma_f32_16x16x32_bf16 v[94:97], v[134:137], v[214:217], v[94:97]
	v_mfma_f32_16x16x32_bf16 v[78:81], v[130:133], v[218:221], v[78:81]
	v_mfma_f32_16x16x32_bf16 v[78:81], v[134:137], v[222:225], v[78:81]
	v_mfma_f32_16x16x32_bf16 v[122:125], v[138:141], v[194:197], v[122:125]
	v_mfma_f32_16x16x32_bf16 v[122:125], v[142:145], v[198:201], v[122:125]
	v_mfma_f32_16x16x32_bf16 v[106:109], v[138:141], v[202:205], v[106:109]
	v_mfma_f32_16x16x32_bf16 v[106:109], v[142:145], v[206:209], v[106:109]
	v_mfma_f32_16x16x32_bf16 v[90:93], v[138:141], v[210:213], v[90:93]
	v_mfma_f32_16x16x32_bf16 v[90:93], v[142:145], v[214:217], v[90:93]
	v_mfma_f32_16x16x32_bf16 v[74:77], v[138:141], v[218:221], v[74:77]
	v_mfma_f32_16x16x32_bf16 v[74:77], v[142:145], v[222:225], v[74:77]
	v_mfma_f32_16x16x32_bf16 v[118:121], v[166:169], v[194:197], v[118:121]
	v_mfma_f32_16x16x32_bf16 v[118:121], v[170:173], v[198:201], v[118:121]
	v_mfma_f32_16x16x32_bf16 v[102:105], v[166:169], v[202:205], v[102:105]
	v_mfma_f32_16x16x32_bf16 v[102:105], v[170:173], v[206:209], v[102:105]
	v_mfma_f32_16x16x32_bf16 v[86:89], v[166:169], v[210:213], v[86:89]
	v_mfma_f32_16x16x32_bf16 v[86:89], v[170:173], v[214:217], v[86:89]
	v_mfma_f32_16x16x32_bf16 v[70:73], v[166:169], v[218:221], v[70:73]
	v_mfma_f32_16x16x32_bf16 v[70:73], v[170:173], v[222:225], v[70:73]
	v_mfma_f32_16x16x32_bf16 v[114:117], v[186:189], v[194:197], v[114:117]
	v_mfma_f32_16x16x32_bf16 v[114:117], v[190:193], v[198:201], v[114:117]
	v_mfma_f32_16x16x32_bf16 v[98:101], v[186:189], v[202:205], v[98:101]
	v_mfma_f32_16x16x32_bf16 v[98:101], v[190:193], v[206:209], v[98:101]
	v_mfma_f32_16x16x32_bf16 v[82:85], v[186:189], v[210:213], v[82:85]
	v_mfma_f32_16x16x32_bf16 v[82:85], v[190:193], v[214:217], v[82:85]
	v_mfma_f32_16x16x32_bf16 v[66:69], v[186:189], v[218:221], v[66:69]
	v_mfma_f32_16x16x32_bf16 v[66:69], v[190:193], v[222:225], v[66:69]
	s_setprio 0
	s_barrier
	s_add_i32 s74, s76, s3
	s_mov_b32 m0, s74
	ds_read_b128 v[194:197], v177 offset:49152
	ds_read_b128 v[198:201], v177 offset:50176
	ds_read_b128 v[202:205], v177 offset:51200
	ds_read_b128 v[206:209], v177 offset:52224
	ds_read_b128 v[210:213], v177 offset:53248
	ds_read_b128 v[214:217], v177 offset:54272
	ds_read_b128 v[218:221], v177 offset:55296
	ds_read_b128 v[222:225], v177 offset:56320
	global_load_lds_dwordx4 v148, s[98:99]
	s_add_i32 m0, s74, 0x2000
	s_add_u32 s74, s82, 0x100080
	s_addc_u32 s75, s83, 0
	s_add_i32 s76, s77, s3
	global_load_lds_dwordx4 v152, s[98:99]
	s_mov_b32 m0, s76
	s_nop 0
	global_load_lds_dwordx4 v148, s[74:75]
	s_add_i32 m0, s76, 0x2000
	s_nop 0
	global_load_lds_dwordx4 v152, s[74:75]
	s_mov_b32 m0, s62
	s_nop 0
	global_load_lds_dwordx4 v146, s[100:101]
	s_mov_b32 m0, s63
	s_nop 0
	global_load_lds_dwordx4 v150, s[100:101]
	s_waitcnt vmcnt(8)
	s_waitcnt lgkmcnt(0)
	s_barrier
	s_setprio 1
	v_mfma_f32_16x16x32_bf16 v[62:65], v[130:133], v[194:197], v[62:65]
	v_mfma_f32_16x16x32_bf16 v[62:65], v[134:137], v[198:201], v[62:65]
	v_mfma_f32_16x16x32_bf16 v[46:49], v[130:133], v[202:205], v[46:49]
	v_mfma_f32_16x16x32_bf16 v[46:49], v[134:137], v[206:209], v[46:49]
	v_mfma_f32_16x16x32_bf16 v[30:33], v[130:133], v[210:213], v[30:33]
	v_mfma_f32_16x16x32_bf16 v[30:33], v[134:137], v[214:217], v[30:33]
	v_mfma_f32_16x16x32_bf16 v[14:17], v[130:133], v[218:221], v[14:17]
	v_mfma_f32_16x16x32_bf16 v[14:17], v[134:137], v[222:225], v[14:17]
	v_mfma_f32_16x16x32_bf16 v[58:61], v[138:141], v[194:197], v[58:61]
	v_mfma_f32_16x16x32_bf16 v[58:61], v[142:145], v[198:201], v[58:61]
	v_mfma_f32_16x16x32_bf16 v[42:45], v[138:141], v[202:205], v[42:45]
	v_mfma_f32_16x16x32_bf16 v[42:45], v[142:145], v[206:209], v[42:45]
	v_mfma_f32_16x16x32_bf16 v[26:29], v[138:141], v[210:213], v[26:29]
	v_mfma_f32_16x16x32_bf16 v[26:29], v[142:145], v[214:217], v[26:29]
	v_mfma_f32_16x16x32_bf16 v[10:13], v[138:141], v[218:221], v[10:13]
	v_mfma_f32_16x16x32_bf16 v[10:13], v[142:145], v[222:225], v[10:13]
	v_mfma_f32_16x16x32_bf16 v[54:57], v[166:169], v[194:197], v[54:57]
	v_mfma_f32_16x16x32_bf16 v[54:57], v[170:173], v[198:201], v[54:57]
	v_mfma_f32_16x16x32_bf16 v[38:41], v[166:169], v[202:205], v[38:41]
	v_mfma_f32_16x16x32_bf16 v[38:41], v[170:173], v[206:209], v[38:41]
	v_mfma_f32_16x16x32_bf16 v[22:25], v[166:169], v[210:213], v[22:25]
	v_mfma_f32_16x16x32_bf16 v[22:25], v[170:173], v[214:217], v[22:25]
	v_mfma_f32_16x16x32_bf16 v[6:9], v[166:169], v[218:221], v[6:9]
	v_mfma_f32_16x16x32_bf16 v[6:9], v[170:173], v[222:225], v[6:9]
	v_mfma_f32_16x16x32_bf16 v[50:53], v[186:189], v[194:197], v[50:53]
	v_mfma_f32_16x16x32_bf16 v[50:53], v[190:193], v[198:201], v[50:53]
	v_mfma_f32_16x16x32_bf16 v[34:37], v[186:189], v[202:205], v[34:37]
	v_mfma_f32_16x16x32_bf16 v[34:37], v[190:193], v[206:209], v[34:37]
	v_mfma_f32_16x16x32_bf16 v[18:21], v[186:189], v[210:213], v[18:21]
	v_mfma_f32_16x16x32_bf16 v[18:21], v[190:193], v[214:217], v[18:21]
	v_mfma_f32_16x16x32_bf16 v[2:5], v[186:189], v[218:221], v[2:5]
	v_mfma_f32_16x16x32_bf16 v[2:5], v[190:193], v[222:225], v[2:5]
	s_setprio 0
	s_barrier
	s_add_i32 s73, s73, 2
	s_add_u32 s50, s50, 0x100
	s_addc_u32 s51, s51, 0
	s_add_u32 s71, s71, 0x100
	s_addc_u32 s72, s72, 0
	s_cmp_gt_u32 s73, 61
	s_cbranch_scc0 .LBB0_2109
	s_and_b64 vcc, exec, s[40:41]
	s_cbranch_vccz .LBB0_2112
	s_barrier

.LBB0_2212:
	ds_read_b128 v[150:153], v162
	ds_read_b128 v[168:171], v162 offset:1024
	ds_read_b128 v[172:175], v162 offset:2048
	ds_read_b128 v[176:179], v162 offset:3072
	ds_read_b128 v[186:189], v163
	ds_read_b128 v[190:193], v163 offset:1024
	ds_read_b128 v[194:197], v163 offset:2048
	ds_read_b128 v[198:201], v163 offset:3072
	s_add_u32 s50, s6, 0xfff00080
	s_addc_u32 s51, s7, -1
	s_cmp_eq_u32 s79, 60
	s_cselect_b32 s81, s45, s51
	s_cselect_b32 s80, s75, s50
	s_cselect_b32 s51, s43, s78
	s_cselect_b32 s50, s76, s77
	s_add_i32 m0, s33, 0xc000
	ds_read_b128 v[202:205], v164
	ds_read_b128 v[206:209], v164 offset:1024
	ds_read_b128 v[210:213], v164 offset:2048
	ds_read_b128 v[214:217], v164 offset:3072
	ds_read_b128 v[218:221], v164 offset:4096
	ds_read_b128 v[222:225], v164 offset:5120
	ds_read_b128 v[226:229], v164 offset:6144
	ds_read_b128 v[230:233], v164 offset:7168
	global_load_lds_dwordx4 v142, s[6:7]
	s_add_i32 m0, s33, 0xe000
	s_nop 0
	global_load_lds_dwordx4 v144, s[6:7]
	s_waitcnt vmcnt(8)
	s_waitcnt lgkmcnt(0)
	s_barrier
	s_setprio 1
	v_mfma_f32_16x16x32_bf16 v[126:129], v[150:153], v[202:205], v[126:129]
	v_mfma_f32_16x16x32_bf16 v[126:129], v[168:171], v[206:209], v[126:129]
	v_mfma_f32_16x16x32_bf16 v[110:113], v[150:153], v[210:213], v[110:113]
	v_mfma_f32_16x16x32_bf16 v[110:113], v[168:171], v[214:217], v[110:113]
	v_mfma_f32_16x16x32_bf16 v[94:97], v[150:153], v[218:221], v[94:97]
	v_mfma_f32_16x16x32_bf16 v[94:97], v[168:171], v[222:225], v[94:97]
	v_mfma_f32_16x16x32_bf16 v[78:81], v[150:153], v[226:229], v[78:81]
	v_mfma_f32_16x16x32_bf16 v[78:81], v[168:171], v[230:233], v[78:81]
	v_mfma_f32_16x16x32_bf16 v[118:121], v[172:175], v[202:205], v[118:121]
	v_mfma_f32_16x16x32_bf16 v[118:121], v[176:179], v[206:209], v[118:121]
	v_mfma_f32_16x16x32_bf16 v[102:105], v[172:175], v[210:213], v[102:105]
	v_mfma_f32_16x16x32_bf16 v[102:105], v[176:179], v[214:217], v[102:105]
	v_mfma_f32_16x16x32_bf16 v[86:89], v[172:175], v[218:221], v[86:89]
	v_mfma_f32_16x16x32_bf16 v[86:89], v[176:179], v[222:225], v[86:89]
	v_mfma_f32_16x16x32_bf16 v[70:73], v[172:175], v[226:229], v[70:73]
	v_mfma_f32_16x16x32_bf16 v[70:73], v[176:179], v[230:233], v[70:73]
	v_mfma_f32_16x16x32_bf16 v[122:125], v[186:189], v[202:205], v[122:125]
	v_mfma_f32_16x16x32_bf16 v[122:125], v[190:193], v[206:209], v[122:125]
	v_mfma_f32_16x16x32_bf16 v[106:109], v[186:189], v[210:213], v[106:109]
	v_mfma_f32_16x16x32_bf16 v[106:109], v[190:193], v[214:217], v[106:109]
	v_mfma_f32_16x16x32_bf16 v[90:93], v[186:189], v[218:221], v[90:93]
	v_mfma_f32_16x16x32_bf16 v[90:93], v[190:193], v[222:225], v[90:93]
	v_mfma_f32_16x16x32_bf16 v[74:77], v[186:189], v[226:229], v[74:77]
	v_mfma_f32_16x16x32_bf16 v[74:77], v[190:193], v[230:233], v[74:77]
	v_mfma_f32_16x16x32_bf16 v[114:117], v[194:197], v[202:205], v[114:117]
	v_mfma_f32_16x16x32_bf16 v[114:117], v[198:201], v[206:209], v[114:117]
	v_mfma_f32_16x16x32_bf16 v[98:101], v[194:197], v[210:213], v[98:101]
	v_mfma_f32_16x16x32_bf16 v[98:101], v[198:201], v[214:217], v[98:101]
	v_mfma_f32_16x16x32_bf16 v[82:85], v[194:197], v[218:221], v[82:85]
	v_mfma_f32_16x16x32_bf16 v[82:85], v[198:201], v[222:225], v[82:85]
	v_mfma_f32_16x16x32_bf16 v[66:69], v[194:197], v[226:229], v[66:69]
	v_mfma_f32_16x16x32_bf16 v[66:69], v[198:201], v[230:233], v[66:69]
	s_setprio 0
	s_barrier
	s_add_i32 s82, s68, s29
	s_add_u32 s98, s50, 0x80
	s_addc_u32 s99, s51, 0
	s_mov_b32 m0, s82
	ds_read_b128 v[202:205], v164 offset:16384
	ds_read_b128 v[206:209], v164 offset:17408
	ds_read_b128 v[210:213], v164 offset:18432
	ds_read_b128 v[214:217], v164 offset:19456
	ds_read_b128 v[218:221], v164 offset:20480
	ds_read_b128 v[222:225], v164 offset:21504
	ds_read_b128 v[226:229], v164 offset:22528
	ds_read_b128 v[230:233], v164 offset:23552
	global_load_lds_dwordx4 v134, s[50:51]
	s_add_i32 m0, s82, 0x2000
	s_add_u32 s82, s50, 0x100000
	s_addc_u32 s83, s51, 0
	s_add_i32 s84, s69, s29
	global_load_lds_dwordx4 v138, s[50:51]
	s_mov_b32 m0, s84
	global_load_lds_dwordx4 v134, s[82:83]
	s_add_i32 m0, s84, 0x2000
	s_nop 0
	global_load_lds_dwordx4 v138, s[82:83]
	s_add_u32 s100, s80, 0x80
	s_addc_u32 s101, s81, 0
	s_mov_b32 m0, s33
	s_nop 0
	global_load_lds_dwordx4 v132, s[80:81]
	s_mov_b32 m0, s35
	s_nop 0
	global_load_lds_dwordx4 v136, s[80:81]
	s_waitcnt vmcnt(8)
	s_waitcnt lgkmcnt(0)
	s_barrier
	s_setprio 1
	v_mfma_f32_16x16x32_bf16 v[62:65], v[150:153], v[202:205], v[62:65]
	v_mfma_f32_16x16x32_bf16 v[62:65], v[168:171], v[206:209], v[62:65]
	v_mfma_f32_16x16x32_bf16 v[46:49], v[150:153], v[210:213], v[46:49]
	v_mfma_f32_16x16x32_bf16 v[46:49], v[168:171], v[214:217], v[46:49]
	v_mfma_f32_16x16x32_bf16 v[30:33], v[150:153], v[218:221], v[30:33]
	v_mfma_f32_16x16x32_bf16 v[30:33], v[168:171], v[222:225], v[30:33]
	v_mfma_f32_16x16x32_bf16 v[14:17], v[150:153], v[226:229], v[14:17]
	v_mfma_f32_16x16x32_bf16 v[14:17], v[168:171], v[230:233], v[14:17]
	v_mfma_f32_16x16x32_bf16 v[54:57], v[172:175], v[202:205], v[54:57]
	v_mfma_f32_16x16x32_bf16 v[54:57], v[176:179], v[206:209], v[54:57]
	v_mfma_f32_16x16x32_bf16 v[38:41], v[172:175], v[210:213], v[38:41]
	v_mfma_f32_16x16x32_bf16 v[38:41], v[176:179], v[214:217], v[38:41]
	v_mfma_f32_16x16x32_bf16 v[22:25], v[172:175], v[218:221], v[22:25]
	v_mfma_f32_16x16x32_bf16 v[22:25], v[176:179], v[222:225], v[22:25]
	v_mfma_f32_16x16x32_bf16 v[6:9], v[172:175], v[226:229], v[6:9]
	v_mfma_f32_16x16x32_bf16 v[6:9], v[176:179], v[230:233], v[6:9]
	v_mfma_f32_16x16x32_bf16 v[58:61], v[186:189], v[202:205], v[58:61]
	v_mfma_f32_16x16x32_bf16 v[58:61], v[190:193], v[206:209], v[58:61]
	v_mfma_f32_16x16x32_bf16 v[42:45], v[186:189], v[210:213], v[42:45]
	v_mfma_f32_16x16x32_bf16 v[42:45], v[190:193], v[214:217], v[42:45]
	v_mfma_f32_16x16x32_bf16 v[26:29], v[186:189], v[218:221], v[26:29]
	v_mfma_f32_16x16x32_bf16 v[26:29], v[190:193], v[222:225], v[26:29]
	v_mfma_f32_16x16x32_bf16 v[10:13], v[186:189], v[226:229], v[10:13]
	v_mfma_f32_16x16x32_bf16 v[10:13], v[190:193], v[230:233], v[10:13]
	v_mfma_f32_16x16x32_bf16 v[50:53], v[194:197], v[202:205], v[50:53]
	v_mfma_f32_16x16x32_bf16 v[50:53], v[198:201], v[206:209], v[50:53]
	v_mfma_f32_16x16x32_bf16 v[34:37], v[194:197], v[210:213], v[34:37]
	v_mfma_f32_16x16x32_bf16 v[34:37], v[198:201], v[214:217], v[34:37]
	v_mfma_f32_16x16x32_bf16 v[18:21], v[194:197], v[218:221], v[18:21]
	v_mfma_f32_16x16x32_bf16 v[18:21], v[198:201], v[222:225], v[18:21]
	v_mfma_f32_16x16x32_bf16 v[2:5], v[194:197], v[226:229], v[2:5]
	v_mfma_f32_16x16x32_bf16 v[2:5], v[198:201], v[230:233], v[2:5]
	s_setprio 0
	s_barrier
	s_add_i32 s82, 0, 0x18000
	v_add_u32_e32 v140, s82, v158
	s_add_i32 s83, 0, 0x1c000
	ds_read_b128 v[150:153], v140
	ds_read_b128 v[168:171], v140 offset:1024
	ds_read_b128 v[172:175], v140 offset:2048
	ds_read_b128 v[176:179], v140 offset:3072
	v_add_u32_e32 v140, s83, v158
	ds_read_b128 v[186:189], v140
	ds_read_b128 v[190:193], v140 offset:1024
	ds_read_b128 v[194:197], v140 offset:2048
	ds_read_b128 v[198:201], v140 offset:3072
	s_add_u32 s80, s80, 0x100000
	s_addc_u32 s81, s81, 0
	s_mov_b32 m0, s59
	ds_read_b128 v[202:205], v164 offset:32768
	ds_read_b128 v[206:209], v164 offset:33792
	ds_read_b128 v[210:213], v164 offset:34816
	ds_read_b128 v[214:217], v164 offset:35840
	ds_read_b128 v[218:221], v164 offset:36864
	ds_read_b128 v[222:225], v164 offset:37888
	ds_read_b128 v[226:229], v164 offset:38912
	ds_read_b128 v[230:233], v164 offset:39936
	global_load_lds_dwordx4 v132, s[80:81]
	s_mov_b32 m0, s62
	s_nop 0
	global_load_lds_dwordx4 v136, s[80:81]
	s_waitcnt vmcnt(8)
	s_waitcnt lgkmcnt(0)
	s_barrier
	s_setprio 1
	v_mfma_f32_16x16x32_bf16 v[126:129], v[150:153], v[202:205], v[126:129]
	v_mfma_f32_16x16x32_bf16 v[126:129], v[168:171], v[206:209], v[126:129]
	v_mfma_f32_16x16x32_bf16 v[110:113], v[150:153], v[210:213], v[110:113]
	v_mfma_f32_16x16x32_bf16 v[110:113], v[168:171], v[214:217], v[110:113]
	v_mfma_f32_16x16x32_bf16 v[94:97], v[150:153], v[218:221], v[94:97]
	v_mfma_f32_16x16x32_bf16 v[94:97], v[168:171], v[222:225], v[94:97]
	v_mfma_f32_16x16x32_bf16 v[78:81], v[150:153], v[226:229], v[78:81]
	v_mfma_f32_16x16x32_bf16 v[78:81], v[168:171], v[230:233], v[78:81]
	v_mfma_f32_16x16x32_bf16 v[118:121], v[172:175], v[202:205], v[118:121]
	v_mfma_f32_16x16x32_bf16 v[118:121], v[176:179], v[206:209], v[118:121]
	v_mfma_f32_16x16x32_bf16 v[102:105], v[172:175], v[210:213], v[102:105]
	v_mfma_f32_16x16x32_bf16 v[102:105], v[176:179], v[214:217], v[102:105]
	v_mfma_f32_16x16x32_bf16 v[86:89], v[172:175], v[218:221], v[86:89]
	v_mfma_f32_16x16x32_bf16 v[86:89], v[176:179], v[222:225], v[86:89]
	v_mfma_f32_16x16x32_bf16 v[70:73], v[172:175], v[226:229], v[70:73]
	v_mfma_f32_16x16x32_bf16 v[70:73], v[176:179], v[230:233], v[70:73]
	v_mfma_f32_16x16x32_bf16 v[122:125], v[186:189], v[202:205], v[122:125]
	v_mfma_f32_16x16x32_bf16 v[122:125], v[190:193], v[206:209], v[122:125]
	v_mfma_f32_16x16x32_bf16 v[106:109], v[186:189], v[210:213], v[106:109]
	v_mfma_f32_16x16x32_bf16 v[106:109], v[190:193], v[214:217], v[106:109]
	v_mfma_f32_16x16x32_bf16 v[90:93], v[186:189], v[218:221], v[90:93]
	v_mfma_f32_16x16x32_bf16 v[90:93], v[190:193], v[222:225], v[90:93]
	v_mfma_f32_16x16x32_bf16 v[74:77], v[186:189], v[226:229], v[74:77]
	v_mfma_f32_16x16x32_bf16 v[74:77], v[190:193], v[230:233], v[74:77]
	v_mfma_f32_16x16x32_bf16 v[114:117], v[194:197], v[202:205], v[114:117]
	v_mfma_f32_16x16x32_bf16 v[114:117], v[198:201], v[206:209], v[114:117]
	v_mfma_f32_16x16x32_bf16 v[98:101], v[194:197], v[210:213], v[98:101]
	v_mfma_f32_16x16x32_bf16 v[98:101], v[198:201], v[214:217], v[98:101]
	v_mfma_f32_16x16x32_bf16 v[82:85], v[194:197], v[218:221], v[82:85]
	v_mfma_f32_16x16x32_bf16 v[82:85], v[198:201], v[222:225], v[82:85]
	v_mfma_f32_16x16x32_bf16 v[66:69], v[194:197], v[226:229], v[66:69]
	v_mfma_f32_16x16x32_bf16 v[66:69], v[198:201], v[230:233], v[66:69]
	s_setprio 0
	s_barrier
	s_add_i32 s80, s82, s29
	s_mov_b32 m0, s80
	ds_read_b128 v[202:205], v164 offset:49152
	ds_read_b128 v[206:209], v164 offset:50176
	ds_read_b128 v[210:213], v164 offset:51200
	ds_read_b128 v[214:217], v164 offset:52224
	ds_read_b128 v[218:221], v164 offset:53248
	ds_read_b128 v[222:225], v164 offset:54272
	ds_read_b128 v[226:229], v164 offset:55296
	ds_read_b128 v[230:233], v164 offset:56320
	global_load_lds_dwordx4 v134, s[98:99]
	s_add_i32 m0, s80, 0x2000
	s_add_u32 s50, s50, 0x100080
	s_addc_u32 s51, s51, 0
	s_add_i32 s80, s83, s29
	global_load_lds_dwordx4 v138, s[98:99]
	s_mov_b32 m0, s80
	s_nop 0
	global_load_lds_dwordx4 v134, s[50:51]
	s_add_i32 m0, s80, 0x2000
	s_nop 0
	global_load_lds_dwordx4 v138, s[50:51]
	s_mov_b32 m0, s65
	s_nop 0
	global_load_lds_dwordx4 v132, s[100:101]
	s_mov_b32 m0, s66
	s_nop 0
	global_load_lds_dwordx4 v136, s[100:101]
	s_waitcnt vmcnt(8)
	s_waitcnt lgkmcnt(0)
	s_barrier
	s_setprio 1
	v_mfma_f32_16x16x32_bf16 v[62:65], v[150:153], v[202:205], v[62:65]
	v_mfma_f32_16x16x32_bf16 v[62:65], v[168:171], v[206:209], v[62:65]
	v_mfma_f32_16x16x32_bf16 v[46:49], v[150:153], v[210:213], v[46:49]
	v_mfma_f32_16x16x32_bf16 v[46:49], v[168:171], v[214:217], v[46:49]
	v_mfma_f32_16x16x32_bf16 v[30:33], v[150:153], v[218:221], v[30:33]
	v_mfma_f32_16x16x32_bf16 v[30:33], v[168:171], v[222:225], v[30:33]
	v_mfma_f32_16x16x32_bf16 v[14:17], v[150:153], v[226:229], v[14:17]
	v_mfma_f32_16x16x32_bf16 v[14:17], v[168:171], v[230:233], v[14:17]
	v_mfma_f32_16x16x32_bf16 v[54:57], v[172:175], v[202:205], v[54:57]
	v_mfma_f32_16x16x32_bf16 v[54:57], v[176:179], v[206:209], v[54:57]
	v_mfma_f32_16x16x32_bf16 v[38:41], v[172:175], v[210:213], v[38:41]
	v_mfma_f32_16x16x32_bf16 v[38:41], v[176:179], v[214:217], v[38:41]
	v_mfma_f32_16x16x32_bf16 v[22:25], v[172:175], v[218:221], v[22:25]
	v_mfma_f32_16x16x32_bf16 v[22:25], v[176:179], v[222:225], v[22:25]
	v_mfma_f32_16x16x32_bf16 v[6:9], v[172:175], v[226:229], v[6:9]
	v_mfma_f32_16x16x32_bf16 v[6:9], v[176:179], v[230:233], v[6:9]
	v_mfma_f32_16x16x32_bf16 v[58:61], v[186:189], v[202:205], v[58:61]
	v_mfma_f32_16x16x32_bf16 v[58:61], v[190:193], v[206:209], v[58:61]
	v_mfma_f32_16x16x32_bf16 v[42:45], v[186:189], v[210:213], v[42:45]
	v_mfma_f32_16x16x32_bf16 v[42:45], v[190:193], v[214:217], v[42:45]
	v_mfma_f32_16x16x32_bf16 v[26:29], v[186:189], v[218:221], v[26:29]
	v_mfma_f32_16x16x32_bf16 v[26:29], v[190:193], v[222:225], v[26:29]
	v_mfma_f32_16x16x32_bf16 v[10:13], v[186:189], v[226:229], v[10:13]
	v_mfma_f32_16x16x32_bf16 v[10:13], v[190:193], v[230:233], v[10:13]
	v_mfma_f32_16x16x32_bf16 v[50:53], v[194:197], v[202:205], v[50:53]
	v_mfma_f32_16x16x32_bf16 v[50:53], v[198:201], v[206:209], v[50:53]
	v_mfma_f32_16x16x32_bf16 v[34:37], v[194:197], v[210:213], v[34:37]
	v_mfma_f32_16x16x32_bf16 v[34:37], v[198:201], v[214:217], v[34:37]
	v_mfma_f32_16x16x32_bf16 v[18:21], v[194:197], v[218:221], v[18:21]
	v_mfma_f32_16x16x32_bf16 v[18:21], v[198:201], v[222:225], v[18:21]
	v_mfma_f32_16x16x32_bf16 v[2:5], v[194:197], v[226:229], v[2:5]
	v_mfma_f32_16x16x32_bf16 v[2:5], v[198:201], v[230:233], v[2:5]
	s_setprio 0
	s_barrier
	s_add_i32 s79, s79, 2
	s_add_u32 s6, s6, 0x100
	s_addc_u32 s7, s7, 0
	s_add_u32 s77, s77, 0x100
	s_addc_u32 s78, s78, 0
	s_cmp_gt_u32 s79, 61
	s_cbranch_scc0 .LBB0_2212
	s_and_b64 vcc, exec, s[40:41]
	s_cbranch_vccz .LBB0_2215
	s_barrier

.LBB0_2340:
	ds_read_b128 v[130:133], v163
	ds_read_b128 v[134:137], v163 offset:1024
	ds_read_b128 v[138:141], v163 offset:2048
	ds_read_b128 v[142:145], v163 offset:3072
	ds_read_b128 v[146:149], v190
	ds_read_b128 v[150:153], v190 offset:1024
	ds_read_b128 v[174:177], v190 offset:2048
	ds_read_b128 v[178:181], v190 offset:3072
	s_add_u32 s42, s40, 0xffd50080
	s_addc_u32 s43, s41, -1
	s_cmpk_eq_i32 s71, 0xa8
	s_cselect_b32 s45, s1, s43
	s_cselect_b32 s44, s0, s42
	s_cselect_b32 s43, s39, s70
	s_cselect_b32 s42, s38, s12
	s_add_i32 m0, s46, 0xc000
	ds_read_b128 v[186:189], v191
	ds_read_b128 v[194:197], v191 offset:1024
	ds_read_b128 v[198:201], v191 offset:2048
	ds_read_b128 v[202:205], v191 offset:3072
	ds_read_b128 v[206:209], v191 offset:4096
	ds_read_b128 v[210:213], v191 offset:5120
	ds_read_b128 v[214:217], v191 offset:6144
	ds_read_b128 v[218:221], v191 offset:7168
	global_load_lds_dwordx4 v166, s[40:41]
	s_add_i32 m0, s46, 0xe000
	s_nop 0
	global_load_lds_dwordx4 v168, s[40:41]
	s_waitcnt vmcnt(8)
	s_waitcnt lgkmcnt(0)
	s_barrier
	s_setprio 1
	v_mfma_f32_16x16x32_bf16 v[126:129], v[130:133], v[186:189], v[126:129]
	v_mfma_f32_16x16x32_bf16 v[126:129], v[134:137], v[194:197], v[126:129]
	v_mfma_f32_16x16x32_bf16 v[110:113], v[130:133], v[198:201], v[110:113]
	v_mfma_f32_16x16x32_bf16 v[110:113], v[134:137], v[202:205], v[110:113]
	v_mfma_f32_16x16x32_bf16 v[94:97], v[130:133], v[206:209], v[94:97]
	v_mfma_f32_16x16x32_bf16 v[94:97], v[134:137], v[210:213], v[94:97]
	v_mfma_f32_16x16x32_bf16 v[78:81], v[130:133], v[214:217], v[78:81]
	v_mfma_f32_16x16x32_bf16 v[78:81], v[134:137], v[218:221], v[78:81]
	v_mfma_f32_16x16x32_bf16 v[122:125], v[138:141], v[186:189], v[122:125]
	v_mfma_f32_16x16x32_bf16 v[122:125], v[142:145], v[194:197], v[122:125]
	v_mfma_f32_16x16x32_bf16 v[106:109], v[138:141], v[198:201], v[106:109]
	v_mfma_f32_16x16x32_bf16 v[106:109], v[142:145], v[202:205], v[106:109]
	v_mfma_f32_16x16x32_bf16 v[90:93], v[138:141], v[206:209], v[90:93]
	v_mfma_f32_16x16x32_bf16 v[90:93], v[142:145], v[210:213], v[90:93]
	v_mfma_f32_16x16x32_bf16 v[74:77], v[138:141], v[214:217], v[74:77]
	v_mfma_f32_16x16x32_bf16 v[74:77], v[142:145], v[218:221], v[74:77]
	v_mfma_f32_16x16x32_bf16 v[118:121], v[146:149], v[186:189], v[118:121]
	v_mfma_f32_16x16x32_bf16 v[118:121], v[150:153], v[194:197], v[118:121]
	v_mfma_f32_16x16x32_bf16 v[102:105], v[146:149], v[198:201], v[102:105]
	v_mfma_f32_16x16x32_bf16 v[102:105], v[150:153], v[202:205], v[102:105]
	v_mfma_f32_16x16x32_bf16 v[86:89], v[146:149], v[206:209], v[86:89]
	v_mfma_f32_16x16x32_bf16 v[86:89], v[150:153], v[210:213], v[86:89]
	v_mfma_f32_16x16x32_bf16 v[70:73], v[146:149], v[214:217], v[70:73]
	v_mfma_f32_16x16x32_bf16 v[70:73], v[150:153], v[218:221], v[70:73]
	v_mfma_f32_16x16x32_bf16 v[114:117], v[174:177], v[186:189], v[114:117]
	v_mfma_f32_16x16x32_bf16 v[114:117], v[178:181], v[194:197], v[114:117]
	v_mfma_f32_16x16x32_bf16 v[98:101], v[174:177], v[198:201], v[98:101]
	v_mfma_f32_16x16x32_bf16 v[98:101], v[178:181], v[202:205], v[98:101]
	v_mfma_f32_16x16x32_bf16 v[82:85], v[174:177], v[206:209], v[82:85]
	v_mfma_f32_16x16x32_bf16 v[82:85], v[178:181], v[210:213], v[82:85]
	v_mfma_f32_16x16x32_bf16 v[66:69], v[174:177], v[214:217], v[66:69]
	v_mfma_f32_16x16x32_bf16 v[66:69], v[178:181], v[218:221], v[66:69]
	s_setprio 0
	s_barrier
	s_add_i32 s72, s65, s35
	s_add_u32 s98, s42, 0x80
	s_addc_u32 s99, s43, 0
	s_mov_b32 m0, s72
	ds_read_b128 v[186:189], v191 offset:16384
	ds_read_b128 v[194:197], v191 offset:17408
	ds_read_b128 v[198:201], v191 offset:18432
	ds_read_b128 v[202:205], v191 offset:19456
	ds_read_b128 v[206:209], v191 offset:20480
	ds_read_b128 v[210:213], v191 offset:21504
	ds_read_b128 v[214:217], v191 offset:22528
	ds_read_b128 v[218:221], v191 offset:23552
	global_load_lds_dwordx4 v156, s[42:43]
	s_add_i32 m0, s72, 0x2000
	s_add_u32 s72, s42, 0x2b0000
	s_addc_u32 s73, s43, 0
	s_add_i32 s74, s66, s35
	global_load_lds_dwordx4 v160, s[42:43]
	s_mov_b32 m0, s74
	global_load_lds_dwordx4 v156, s[72:73]
	s_add_i32 m0, s74, 0x2000
	s_nop 0
	global_load_lds_dwordx4 v160, s[72:73]
	s_add_u32 s100, s44, 0x80
	s_addc_u32 s101, s45, 0
	s_mov_b32 m0, s46
	s_nop 0
	global_load_lds_dwordx4 v154, s[44:45]
	s_mov_b32 m0, s47
	s_nop 0
	global_load_lds_dwordx4 v158, s[44:45]
	s_waitcnt vmcnt(8)
	s_waitcnt lgkmcnt(0)
	s_barrier
	s_setprio 1
	v_mfma_f32_16x16x32_bf16 v[62:65], v[130:133], v[186:189], v[62:65]
	v_mfma_f32_16x16x32_bf16 v[62:65], v[134:137], v[194:197], v[62:65]
	v_mfma_f32_16x16x32_bf16 v[46:49], v[130:133], v[198:201], v[46:49]
	v_mfma_f32_16x16x32_bf16 v[46:49], v[134:137], v[202:205], v[46:49]
	v_mfma_f32_16x16x32_bf16 v[30:33], v[130:133], v[206:209], v[30:33]
	v_mfma_f32_16x16x32_bf16 v[30:33], v[134:137], v[210:213], v[30:33]
	v_mfma_f32_16x16x32_bf16 v[14:17], v[130:133], v[214:217], v[14:17]
	v_mfma_f32_16x16x32_bf16 v[14:17], v[134:137], v[218:221], v[14:17]
	v_mfma_f32_16x16x32_bf16 v[58:61], v[138:141], v[186:189], v[58:61]
	v_mfma_f32_16x16x32_bf16 v[58:61], v[142:145], v[194:197], v[58:61]
	v_mfma_f32_16x16x32_bf16 v[42:45], v[138:141], v[198:201], v[42:45]
	v_mfma_f32_16x16x32_bf16 v[42:45], v[142:145], v[202:205], v[42:45]
	v_mfma_f32_16x16x32_bf16 v[26:29], v[138:141], v[206:209], v[26:29]
	v_mfma_f32_16x16x32_bf16 v[26:29], v[142:145], v[210:213], v[26:29]
	v_mfma_f32_16x16x32_bf16 v[10:13], v[138:141], v[214:217], v[10:13]
	v_mfma_f32_16x16x32_bf16 v[10:13], v[142:145], v[218:221], v[10:13]
	v_mfma_f32_16x16x32_bf16 v[54:57], v[146:149], v[186:189], v[54:57]
	v_mfma_f32_16x16x32_bf16 v[54:57], v[150:153], v[194:197], v[54:57]
	v_mfma_f32_16x16x32_bf16 v[38:41], v[146:149], v[198:201], v[38:41]
	v_mfma_f32_16x16x32_bf16 v[38:41], v[150:153], v[202:205], v[38:41]
	v_mfma_f32_16x16x32_bf16 v[22:25], v[146:149], v[206:209], v[22:25]
	v_mfma_f32_16x16x32_bf16 v[22:25], v[150:153], v[210:213], v[22:25]
	v_mfma_f32_16x16x32_bf16 v[6:9], v[146:149], v[214:217], v[6:9]
	v_mfma_f32_16x16x32_bf16 v[6:9], v[150:153], v[218:221], v[6:9]
	v_mfma_f32_16x16x32_bf16 v[50:53], v[174:177], v[186:189], v[50:53]
	v_mfma_f32_16x16x32_bf16 v[50:53], v[178:181], v[194:197], v[50:53]
	v_mfma_f32_16x16x32_bf16 v[34:37], v[174:177], v[198:201], v[34:37]
	v_mfma_f32_16x16x32_bf16 v[34:37], v[178:181], v[202:205], v[34:37]
	v_mfma_f32_16x16x32_bf16 v[18:21], v[174:177], v[206:209], v[18:21]
	v_mfma_f32_16x16x32_bf16 v[18:21], v[178:181], v[210:213], v[18:21]
	v_mfma_f32_16x16x32_bf16 v[2:5], v[174:177], v[214:217], v[2:5]
	v_mfma_f32_16x16x32_bf16 v[2:5], v[178:181], v[218:221], v[2:5]
	s_setprio 0
	s_barrier
	s_add_i32 s72, 0, 0x18000
	s_add_i32 s73, 0, 0x1c000
	v_add_u32_e32 v142, s72, v183
	v_add_u32_e32 v178, s73, v183
	ds_read_b128 v[130:133], v142
	ds_read_b128 v[134:137], v142 offset:1024
	ds_read_b128 v[138:141], v142 offset:2048
	ds_read_b128 v[142:145], v142 offset:3072
	ds_read_b128 v[146:149], v178
	ds_read_b128 v[150:153], v178 offset:1024
	ds_read_b128 v[174:177], v178 offset:2048
	ds_read_b128 v[178:181], v178 offset:3072
	s_add_u32 s44, s44, 0x2b0000
	s_addc_u32 s45, s45, 0
	s_mov_b32 m0, s48
	ds_read_b128 v[186:189], v191 offset:32768
	ds_read_b128 v[194:197], v191 offset:33792
	ds_read_b128 v[198:201], v191 offset:34816
	ds_read_b128 v[202:205], v191 offset:35840
	ds_read_b128 v[206:209], v191 offset:36864
	ds_read_b128 v[210:213], v191 offset:37888
	ds_read_b128 v[214:217], v191 offset:38912
	ds_read_b128 v[218:221], v191 offset:39936
	global_load_lds_dwordx4 v154, s[44:45]
	s_mov_b32 m0, s49
	s_nop 0
	global_load_lds_dwordx4 v158, s[44:45]
	s_waitcnt vmcnt(8)
	s_waitcnt lgkmcnt(0)
	s_barrier
	s_setprio 1
	v_mfma_f32_16x16x32_bf16 v[126:129], v[130:133], v[186:189], v[126:129]
	v_mfma_f32_16x16x32_bf16 v[126:129], v[134:137], v[194:197], v[126:129]
	v_mfma_f32_16x16x32_bf16 v[110:113], v[130:133], v[198:201], v[110:113]
	v_mfma_f32_16x16x32_bf16 v[110:113], v[134:137], v[202:205], v[110:113]
	v_mfma_f32_16x16x32_bf16 v[94:97], v[130:133], v[206:209], v[94:97]
	v_mfma_f32_16x16x32_bf16 v[94:97], v[134:137], v[210:213], v[94:97]
	v_mfma_f32_16x16x32_bf16 v[78:81], v[130:133], v[214:217], v[78:81]
	v_mfma_f32_16x16x32_bf16 v[78:81], v[134:137], v[218:221], v[78:81]
	v_mfma_f32_16x16x32_bf16 v[122:125], v[138:141], v[186:189], v[122:125]
	v_mfma_f32_16x16x32_bf16 v[122:125], v[142:145], v[194:197], v[122:125]
	v_mfma_f32_16x16x32_bf16 v[106:109], v[138:141], v[198:201], v[106:109]
	v_mfma_f32_16x16x32_bf16 v[106:109], v[142:145], v[202:205], v[106:109]
	v_mfma_f32_16x16x32_bf16 v[90:93], v[138:141], v[206:209], v[90:93]
	v_mfma_f32_16x16x32_bf16 v[90:93], v[142:145], v[210:213], v[90:93]
	v_mfma_f32_16x16x32_bf16 v[74:77], v[138:141], v[214:217], v[74:77]
	v_mfma_f32_16x16x32_bf16 v[74:77], v[142:145], v[218:221], v[74:77]
	v_mfma_f32_16x16x32_bf16 v[118:121], v[146:149], v[186:189], v[118:121]
	v_mfma_f32_16x16x32_bf16 v[118:121], v[150:153], v[194:197], v[118:121]
	v_mfma_f32_16x16x32_bf16 v[102:105], v[146:149], v[198:201], v[102:105]
	v_mfma_f32_16x16x32_bf16 v[102:105], v[150:153], v[202:205], v[102:105]
	v_mfma_f32_16x16x32_bf16 v[86:89], v[146:149], v[206:209], v[86:89]
	v_mfma_f32_16x16x32_bf16 v[86:89], v[150:153], v[210:213], v[86:89]
	v_mfma_f32_16x16x32_bf16 v[70:73], v[146:149], v[214:217], v[70:73]
	v_mfma_f32_16x16x32_bf16 v[70:73], v[150:153], v[218:221], v[70:73]
	v_mfma_f32_16x16x32_bf16 v[114:117], v[174:177], v[186:189], v[114:117]
	v_mfma_f32_16x16x32_bf16 v[114:117], v[178:181], v[194:197], v[114:117]
	v_mfma_f32_16x16x32_bf16 v[98:101], v[174:177], v[198:201], v[98:101]
	v_mfma_f32_16x16x32_bf16 v[98:101], v[178:181], v[202:205], v[98:101]
	v_mfma_f32_16x16x32_bf16 v[82:85], v[174:177], v[206:209], v[82:85]
	v_mfma_f32_16x16x32_bf16 v[82:85], v[178:181], v[210:213], v[82:85]
	v_mfma_f32_16x16x32_bf16 v[66:69], v[174:177], v[214:217], v[66:69]
	v_mfma_f32_16x16x32_bf16 v[66:69], v[178:181], v[218:221], v[66:69]
	s_setprio 0
	s_barrier
	s_add_i32 s44, s72, s35
	s_mov_b32 m0, s44
	ds_read_b128 v[186:189], v191 offset:49152
	ds_read_b128 v[194:197], v191 offset:50176
	ds_read_b128 v[198:201], v191 offset:51200
	ds_read_b128 v[202:205], v191 offset:52224
	ds_read_b128 v[206:209], v191 offset:53248
	ds_read_b128 v[210:213], v191 offset:54272
	ds_read_b128 v[214:217], v191 offset:55296
	ds_read_b128 v[218:221], v191 offset:56320
	global_load_lds_dwordx4 v156, s[98:99]
	s_add_i32 m0, s44, 0x2000
	s_add_u32 s42, s42, 0x2b0080
	s_addc_u32 s43, s43, 0
	s_add_i32 s44, s73, s35
	global_load_lds_dwordx4 v160, s[98:99]
	s_mov_b32 m0, s44
	s_nop 0
	global_load_lds_dwordx4 v156, s[42:43]
	s_add_i32 m0, s44, 0x2000
	s_nop 0
	global_load_lds_dwordx4 v160, s[42:43]
	s_mov_b32 m0, s51
	s_nop 0
	global_load_lds_dwordx4 v154, s[100:101]
	s_mov_b32 m0, s59
	s_nop 0
	global_load_lds_dwordx4 v158, s[100:101]
	s_waitcnt vmcnt(8)
	s_waitcnt lgkmcnt(0)
	s_barrier
	s_setprio 1
	v_mfma_f32_16x16x32_bf16 v[62:65], v[130:133], v[186:189], v[62:65]
	v_mfma_f32_16x16x32_bf16 v[62:65], v[134:137], v[194:197], v[62:65]
	v_mfma_f32_16x16x32_bf16 v[46:49], v[130:133], v[198:201], v[46:49]
	v_mfma_f32_16x16x32_bf16 v[46:49], v[134:137], v[202:205], v[46:49]
	v_mfma_f32_16x16x32_bf16 v[30:33], v[130:133], v[206:209], v[30:33]
	v_mfma_f32_16x16x32_bf16 v[30:33], v[134:137], v[210:213], v[30:33]
	v_mfma_f32_16x16x32_bf16 v[14:17], v[130:133], v[214:217], v[14:17]
	v_mfma_f32_16x16x32_bf16 v[14:17], v[134:137], v[218:221], v[14:17]
	v_mfma_f32_16x16x32_bf16 v[58:61], v[138:141], v[186:189], v[58:61]
	v_mfma_f32_16x16x32_bf16 v[58:61], v[142:145], v[194:197], v[58:61]
	v_mfma_f32_16x16x32_bf16 v[42:45], v[138:141], v[198:201], v[42:45]
	v_mfma_f32_16x16x32_bf16 v[42:45], v[142:145], v[202:205], v[42:45]
	v_mfma_f32_16x16x32_bf16 v[26:29], v[138:141], v[206:209], v[26:29]
	v_mfma_f32_16x16x32_bf16 v[26:29], v[142:145], v[210:213], v[26:29]
	v_mfma_f32_16x16x32_bf16 v[10:13], v[138:141], v[214:217], v[10:13]
	v_mfma_f32_16x16x32_bf16 v[10:13], v[142:145], v[218:221], v[10:13]
	v_mfma_f32_16x16x32_bf16 v[54:57], v[146:149], v[186:189], v[54:57]
	v_mfma_f32_16x16x32_bf16 v[54:57], v[150:153], v[194:197], v[54:57]
	v_mfma_f32_16x16x32_bf16 v[38:41], v[146:149], v[198:201], v[38:41]
	v_mfma_f32_16x16x32_bf16 v[38:41], v[150:153], v[202:205], v[38:41]
	v_mfma_f32_16x16x32_bf16 v[22:25], v[146:149], v[206:209], v[22:25]
	v_mfma_f32_16x16x32_bf16 v[22:25], v[150:153], v[210:213], v[22:25]
	v_mfma_f32_16x16x32_bf16 v[6:9], v[146:149], v[214:217], v[6:9]
	v_mfma_f32_16x16x32_bf16 v[6:9], v[150:153], v[218:221], v[6:9]
	v_mfma_f32_16x16x32_bf16 v[50:53], v[174:177], v[186:189], v[50:53]
	v_mfma_f32_16x16x32_bf16 v[50:53], v[178:181], v[194:197], v[50:53]
	v_mfma_f32_16x16x32_bf16 v[34:37], v[174:177], v[198:201], v[34:37]
	v_mfma_f32_16x16x32_bf16 v[34:37], v[178:181], v[202:205], v[34:37]
	v_mfma_f32_16x16x32_bf16 v[18:21], v[174:177], v[206:209], v[18:21]
	v_mfma_f32_16x16x32_bf16 v[18:21], v[178:181], v[210:213], v[18:21]
	v_mfma_f32_16x16x32_bf16 v[2:5], v[174:177], v[214:217], v[2:5]
	v_mfma_f32_16x16x32_bf16 v[2:5], v[178:181], v[218:221], v[2:5]
	s_setprio 0
	s_barrier
	s_add_i32 s71, s71, 2
	s_add_u32 s40, s40, 0x100
	s_addc_u32 s41, s41, 0
	s_add_u32 s12, s12, 0x100
	s_addc_u32 s70, s70, 0
	s_cmpk_gt_u32 s71, 0xa9
	s_cbranch_scc0 .LBB0_2340
	s_and_b64 vcc, exec, s[36:37]
	s_cbranch_vccz .LBB0_2343
	s_barrier

.LBB0_2464:
	ds_read_b128 v[150:153], v167
	ds_read_b128 v[172:175], v167 offset:1024
	ds_read_b128 v[176:179], v167 offset:2048
	ds_read_b128 v[184:187], v167 offset:3072
	ds_read_b128 v[188:191], v168
	ds_read_b128 v[192:195], v168 offset:1024
	ds_read_b128 v[196:199], v168 offset:2048
	ds_read_b128 v[200:203], v168 offset:3072
	s_add_u32 s74, s6, 0xfff00080
	s_addc_u32 s75, s7, -1
	s_cmp_eq_u32 s87, 60
	s_cselect_b32 s77, s47, s75
	s_cselect_b32 s76, s83, s74
	s_cselect_b32 s75, s45, s86
	s_cselect_b32 s74, s84, s85
	s_add_i32 m0, s59, 0xc000
	ds_read_b128 v[204:207], v169
	ds_read_b128 v[208:211], v169 offset:1024
	ds_read_b128 v[212:215], v169 offset:2048
	ds_read_b128 v[216:219], v169 offset:3072
	ds_read_b128 v[220:223], v169 offset:4096
	ds_read_b128 v[224:227], v169 offset:5120
	ds_read_b128 v[228:231], v169 offset:6144
	ds_read_b128 v[232:235], v169 offset:7168
	global_load_lds_dwordx4 v142, s[6:7]
	s_add_i32 m0, s59, 0xe000
	s_nop 0
	global_load_lds_dwordx4 v144, s[6:7]
	s_waitcnt vmcnt(8)
	s_waitcnt lgkmcnt(0)
	s_barrier
	s_setprio 1
	v_mfma_f32_16x16x32_bf16 v[126:129], v[150:153], v[204:207], v[126:129]
	v_mfma_f32_16x16x32_bf16 v[126:129], v[172:175], v[208:211], v[126:129]
	v_mfma_f32_16x16x32_bf16 v[110:113], v[150:153], v[212:215], v[110:113]
	v_mfma_f32_16x16x32_bf16 v[110:113], v[172:175], v[216:219], v[110:113]
	v_mfma_f32_16x16x32_bf16 v[94:97], v[150:153], v[220:223], v[94:97]
	v_mfma_f32_16x16x32_bf16 v[94:97], v[172:175], v[224:227], v[94:97]
	v_mfma_f32_16x16x32_bf16 v[78:81], v[150:153], v[228:231], v[78:81]
	v_mfma_f32_16x16x32_bf16 v[78:81], v[172:175], v[232:235], v[78:81]
	v_mfma_f32_16x16x32_bf16 v[122:125], v[176:179], v[204:207], v[122:125]
	v_mfma_f32_16x16x32_bf16 v[122:125], v[184:187], v[208:211], v[122:125]
	v_mfma_f32_16x16x32_bf16 v[106:109], v[176:179], v[212:215], v[106:109]
	v_mfma_f32_16x16x32_bf16 v[106:109], v[184:187], v[216:219], v[106:109]
	v_mfma_f32_16x16x32_bf16 v[90:93], v[176:179], v[220:223], v[90:93]
	v_mfma_f32_16x16x32_bf16 v[90:93], v[184:187], v[224:227], v[90:93]
	v_mfma_f32_16x16x32_bf16 v[74:77], v[176:179], v[228:231], v[74:77]
	v_mfma_f32_16x16x32_bf16 v[74:77], v[184:187], v[232:235], v[74:77]
	v_mfma_f32_16x16x32_bf16 v[118:121], v[188:191], v[204:207], v[118:121]
	v_mfma_f32_16x16x32_bf16 v[118:121], v[192:195], v[208:211], v[118:121]
	v_mfma_f32_16x16x32_bf16 v[102:105], v[188:191], v[212:215], v[102:105]
	v_mfma_f32_16x16x32_bf16 v[102:105], v[192:195], v[216:219], v[102:105]
	v_mfma_f32_16x16x32_bf16 v[86:89], v[188:191], v[220:223], v[86:89]
	v_mfma_f32_16x16x32_bf16 v[86:89], v[192:195], v[224:227], v[86:89]
	v_mfma_f32_16x16x32_bf16 v[70:73], v[188:191], v[228:231], v[70:73]
	v_mfma_f32_16x16x32_bf16 v[70:73], v[192:195], v[232:235], v[70:73]
	v_mfma_f32_16x16x32_bf16 v[114:117], v[196:199], v[204:207], v[114:117]
	v_mfma_f32_16x16x32_bf16 v[114:117], v[200:203], v[208:211], v[114:117]
	v_mfma_f32_16x16x32_bf16 v[98:101], v[196:199], v[212:215], v[98:101]
	v_mfma_f32_16x16x32_bf16 v[98:101], v[200:203], v[216:219], v[98:101]
	v_mfma_f32_16x16x32_bf16 v[82:85], v[196:199], v[220:223], v[82:85]
	v_mfma_f32_16x16x32_bf16 v[82:85], v[200:203], v[224:227], v[82:85]
	v_mfma_f32_16x16x32_bf16 v[66:69], v[196:199], v[228:231], v[66:69]
	v_mfma_f32_16x16x32_bf16 v[66:69], v[200:203], v[232:235], v[66:69]
	s_setprio 0
	s_barrier
	s_add_i32 s88, s70, s27
	s_add_u32 s98, s74, 0x80
	s_addc_u32 s99, s75, 0
	s_mov_b32 m0, s88
	ds_read_b128 v[204:207], v169 offset:16384
	ds_read_b128 v[208:211], v169 offset:17408
	ds_read_b128 v[212:215], v169 offset:18432
	ds_read_b128 v[216:219], v169 offset:19456
	ds_read_b128 v[220:223], v169 offset:20480
	ds_read_b128 v[224:227], v169 offset:21504
	ds_read_b128 v[228:231], v169 offset:22528
	ds_read_b128 v[232:235], v169 offset:23552
	global_load_lds_dwordx4 v132, s[74:75]
	s_add_i32 m0, s88, 0x2000
	s_add_u32 s88, s74, 0x100000
	s_addc_u32 s89, s75, 0
	s_add_i32 s90, s71, s27
	global_load_lds_dwordx4 v136, s[74:75]
	s_mov_b32 m0, s90
	global_load_lds_dwordx4 v132, s[88:89]
	s_add_i32 m0, s90, 0x2000
	s_nop 0
	global_load_lds_dwordx4 v136, s[88:89]
	s_add_u32 s100, s76, 0x80
	s_addc_u32 s101, s77, 0
	s_mov_b32 m0, s59
	s_nop 0
	global_load_lds_dwordx4 v130, s[76:77]
	s_mov_b32 m0, s62
	s_nop 0
	global_load_lds_dwordx4 v134, s[76:77]
	s_waitcnt vmcnt(8)
	s_waitcnt lgkmcnt(0)
	s_barrier
	s_setprio 1
	v_mfma_f32_16x16x32_bf16 v[62:65], v[150:153], v[204:207], v[62:65]
	v_mfma_f32_16x16x32_bf16 v[62:65], v[172:175], v[208:211], v[62:65]
	v_mfma_f32_16x16x32_bf16 v[50:53], v[150:153], v[212:215], v[50:53]
	v_mfma_f32_16x16x32_bf16 v[50:53], v[172:175], v[216:219], v[50:53]
	v_mfma_f32_16x16x32_bf16 v[34:37], v[150:153], v[220:223], v[34:37]
	v_mfma_f32_16x16x32_bf16 v[34:37], v[172:175], v[224:227], v[34:37]
	v_mfma_f32_16x16x32_bf16 v[18:21], v[150:153], v[228:231], v[18:21]
	v_mfma_f32_16x16x32_bf16 v[18:21], v[172:175], v[232:235], v[18:21]
	v_mfma_f32_16x16x32_bf16 v[58:61], v[176:179], v[204:207], v[58:61]
	v_mfma_f32_16x16x32_bf16 v[58:61], v[184:187], v[208:211], v[58:61]
	v_mfma_f32_16x16x32_bf16 v[42:45], v[176:179], v[212:215], v[42:45]
	v_mfma_f32_16x16x32_bf16 v[42:45], v[184:187], v[216:219], v[42:45]
	v_mfma_f32_16x16x32_bf16 v[26:29], v[176:179], v[220:223], v[26:29]
	v_mfma_f32_16x16x32_bf16 v[26:29], v[184:187], v[224:227], v[26:29]
	v_mfma_f32_16x16x32_bf16 v[10:13], v[176:179], v[228:231], v[10:13]
	v_mfma_f32_16x16x32_bf16 v[10:13], v[184:187], v[232:235], v[10:13]
	v_mfma_f32_16x16x32_bf16 v[54:57], v[188:191], v[204:207], v[54:57]
	v_mfma_f32_16x16x32_bf16 v[54:57], v[192:195], v[208:211], v[54:57]
	v_mfma_f32_16x16x32_bf16 v[38:41], v[188:191], v[212:215], v[38:41]
	v_mfma_f32_16x16x32_bf16 v[38:41], v[192:195], v[216:219], v[38:41]
	v_mfma_f32_16x16x32_bf16 v[22:25], v[188:191], v[220:223], v[22:25]
	v_mfma_f32_16x16x32_bf16 v[22:25], v[192:195], v[224:227], v[22:25]
	v_mfma_f32_16x16x32_bf16 v[6:9], v[188:191], v[228:231], v[6:9]
	v_mfma_f32_16x16x32_bf16 v[6:9], v[192:195], v[232:235], v[6:9]
	v_mfma_f32_16x16x32_bf16 v[46:49], v[196:199], v[204:207], v[46:49]
	v_mfma_f32_16x16x32_bf16 v[46:49], v[200:203], v[208:211], v[46:49]
	v_mfma_f32_16x16x32_bf16 v[30:33], v[196:199], v[212:215], v[30:33]
	v_mfma_f32_16x16x32_bf16 v[30:33], v[200:203], v[216:219], v[30:33]
	v_mfma_f32_16x16x32_bf16 v[14:17], v[196:199], v[220:223], v[14:17]
	v_mfma_f32_16x16x32_bf16 v[14:17], v[200:203], v[224:227], v[14:17]
	v_mfma_f32_16x16x32_bf16 v[2:5], v[196:199], v[228:231], v[2:5]
	v_mfma_f32_16x16x32_bf16 v[2:5], v[200:203], v[232:235], v[2:5]
	s_setprio 0
	s_barrier
	s_add_i32 s88, 0, 0x18000
	v_add_u32_e32 v140, s88, v163
	s_add_i32 s89, 0, 0x1c000
	ds_read_b128 v[150:153], v140
	ds_read_b128 v[172:175], v140 offset:1024
	ds_read_b128 v[176:179], v140 offset:2048
	ds_read_b128 v[184:187], v140 offset:3072
	v_add_u32_e32 v140, s89, v163
	ds_read_b128 v[188:191], v140
	ds_read_b128 v[192:195], v140 offset:1024
	ds_read_b128 v[196:199], v140 offset:2048
	ds_read_b128 v[200:203], v140 offset:3072
	s_add_u32 s76, s76, 0x100000
	s_addc_u32 s77, s77, 0
	s_mov_b32 m0, s63
	ds_read_b128 v[204:207], v169 offset:32768
	ds_read_b128 v[208:211], v169 offset:33792
	ds_read_b128 v[212:215], v169 offset:34816
	ds_read_b128 v[216:219], v169 offset:35840
	ds_read_b128 v[220:223], v169 offset:36864
	ds_read_b128 v[224:227], v169 offset:37888
	ds_read_b128 v[228:231], v169 offset:38912
	ds_read_b128 v[232:235], v169 offset:39936
	global_load_lds_dwordx4 v130, s[76:77]
	s_mov_b32 m0, s65
	s_nop 0
	global_load_lds_dwordx4 v134, s[76:77]
	s_waitcnt vmcnt(8)
	s_waitcnt lgkmcnt(0)
	s_barrier
	s_setprio 1
	v_mfma_f32_16x16x32_bf16 v[126:129], v[150:153], v[204:207], v[126:129]
	v_mfma_f32_16x16x32_bf16 v[126:129], v[172:175], v[208:211], v[126:129]
	v_mfma_f32_16x16x32_bf16 v[110:113], v[150:153], v[212:215], v[110:113]
	v_mfma_f32_16x16x32_bf16 v[110:113], v[172:175], v[216:219], v[110:113]
	v_mfma_f32_16x16x32_bf16 v[94:97], v[150:153], v[220:223], v[94:97]
	v_mfma_f32_16x16x32_bf16 v[94:97], v[172:175], v[224:227], v[94:97]
	v_mfma_f32_16x16x32_bf16 v[78:81], v[150:153], v[228:231], v[78:81]
	v_mfma_f32_16x16x32_bf16 v[78:81], v[172:175], v[232:235], v[78:81]
	v_mfma_f32_16x16x32_bf16 v[122:125], v[176:179], v[204:207], v[122:125]
	v_mfma_f32_16x16x32_bf16 v[122:125], v[184:187], v[208:211], v[122:125]
	v_mfma_f32_16x16x32_bf16 v[106:109], v[176:179], v[212:215], v[106:109]
	v_mfma_f32_16x16x32_bf16 v[106:109], v[184:187], v[216:219], v[106:109]
	v_mfma_f32_16x16x32_bf16 v[90:93], v[176:179], v[220:223], v[90:93]
	v_mfma_f32_16x16x32_bf16 v[90:93], v[184:187], v[224:227], v[90:93]
	v_mfma_f32_16x16x32_bf16 v[74:77], v[176:179], v[228:231], v[74:77]
	v_mfma_f32_16x16x32_bf16 v[74:77], v[184:187], v[232:235], v[74:77]
	v_mfma_f32_16x16x32_bf16 v[118:121], v[188:191], v[204:207], v[118:121]
	v_mfma_f32_16x16x32_bf16 v[118:121], v[192:195], v[208:211], v[118:121]
	v_mfma_f32_16x16x32_bf16 v[102:105], v[188:191], v[212:215], v[102:105]
	v_mfma_f32_16x16x32_bf16 v[102:105], v[192:195], v[216:219], v[102:105]
	v_mfma_f32_16x16x32_bf16 v[86:89], v[188:191], v[220:223], v[86:89]
	v_mfma_f32_16x16x32_bf16 v[86:89], v[192:195], v[224:227], v[86:89]
	v_mfma_f32_16x16x32_bf16 v[70:73], v[188:191], v[228:231], v[70:73]
	v_mfma_f32_16x16x32_bf16 v[70:73], v[192:195], v[232:235], v[70:73]
	v_mfma_f32_16x16x32_bf16 v[114:117], v[196:199], v[204:207], v[114:117]
	v_mfma_f32_16x16x32_bf16 v[114:117], v[200:203], v[208:211], v[114:117]
	v_mfma_f32_16x16x32_bf16 v[98:101], v[196:199], v[212:215], v[98:101]
	v_mfma_f32_16x16x32_bf16 v[98:101], v[200:203], v[216:219], v[98:101]
	v_mfma_f32_16x16x32_bf16 v[82:85], v[196:199], v[220:223], v[82:85]
	v_mfma_f32_16x16x32_bf16 v[82:85], v[200:203], v[224:227], v[82:85]
	v_mfma_f32_16x16x32_bf16 v[66:69], v[196:199], v[228:231], v[66:69]
	v_mfma_f32_16x16x32_bf16 v[66:69], v[200:203], v[232:235], v[66:69]
	s_setprio 0
	s_barrier
	s_add_i32 s76, s88, s27
	s_mov_b32 m0, s76
	ds_read_b128 v[204:207], v169 offset:49152
	ds_read_b128 v[208:211], v169 offset:50176
	ds_read_b128 v[212:215], v169 offset:51200
	ds_read_b128 v[216:219], v169 offset:52224
	ds_read_b128 v[220:223], v169 offset:53248
	ds_read_b128 v[224:227], v169 offset:54272
	ds_read_b128 v[228:231], v169 offset:55296
	ds_read_b128 v[232:235], v169 offset:56320
	global_load_lds_dwordx4 v132, s[98:99]
	s_add_i32 m0, s76, 0x2000
	s_add_u32 s74, s74, 0x100080
	s_addc_u32 s75, s75, 0
	s_add_i32 s76, s89, s27
	global_load_lds_dwordx4 v136, s[98:99]
	s_mov_b32 m0, s76
	s_nop 0
	global_load_lds_dwordx4 v132, s[74:75]
	s_add_i32 m0, s76, 0x2000
	s_nop 0
	global_load_lds_dwordx4 v136, s[74:75]
	s_mov_b32 m0, s67
	s_nop 0
	global_load_lds_dwordx4 v130, s[100:101]
	s_mov_b32 m0, s68
	s_nop 0
	global_load_lds_dwordx4 v134, s[100:101]
	s_waitcnt vmcnt(8)
	s_waitcnt lgkmcnt(0)
	s_barrier
	s_setprio 1
	v_mfma_f32_16x16x32_bf16 v[62:65], v[150:153], v[204:207], v[62:65]
	v_mfma_f32_16x16x32_bf16 v[62:65], v[172:175], v[208:211], v[62:65]
	v_mfma_f32_16x16x32_bf16 v[50:53], v[150:153], v[212:215], v[50:53]
	v_mfma_f32_16x16x32_bf16 v[50:53], v[172:175], v[216:219], v[50:53]
	v_mfma_f32_16x16x32_bf16 v[34:37], v[150:153], v[220:223], v[34:37]
	v_mfma_f32_16x16x32_bf16 v[34:37], v[172:175], v[224:227], v[34:37]
	v_mfma_f32_16x16x32_bf16 v[18:21], v[150:153], v[228:231], v[18:21]
	v_mfma_f32_16x16x32_bf16 v[18:21], v[172:175], v[232:235], v[18:21]
	v_mfma_f32_16x16x32_bf16 v[58:61], v[176:179], v[204:207], v[58:61]
	v_mfma_f32_16x16x32_bf16 v[58:61], v[184:187], v[208:211], v[58:61]
	v_mfma_f32_16x16x32_bf16 v[42:45], v[176:179], v[212:215], v[42:45]
	v_mfma_f32_16x16x32_bf16 v[42:45], v[184:187], v[216:219], v[42:45]
	v_mfma_f32_16x16x32_bf16 v[26:29], v[176:179], v[220:223], v[26:29]
	v_mfma_f32_16x16x32_bf16 v[26:29], v[184:187], v[224:227], v[26:29]
	v_mfma_f32_16x16x32_bf16 v[10:13], v[176:179], v[228:231], v[10:13]
	v_mfma_f32_16x16x32_bf16 v[10:13], v[184:187], v[232:235], v[10:13]
	v_mfma_f32_16x16x32_bf16 v[54:57], v[188:191], v[204:207], v[54:57]
	v_mfma_f32_16x16x32_bf16 v[54:57], v[192:195], v[208:211], v[54:57]
	v_mfma_f32_16x16x32_bf16 v[38:41], v[188:191], v[212:215], v[38:41]
	v_mfma_f32_16x16x32_bf16 v[38:41], v[192:195], v[216:219], v[38:41]
	v_mfma_f32_16x16x32_bf16 v[22:25], v[188:191], v[220:223], v[22:25]
	v_mfma_f32_16x16x32_bf16 v[22:25], v[192:195], v[224:227], v[22:25]
	v_mfma_f32_16x16x32_bf16 v[6:9], v[188:191], v[228:231], v[6:9]
	v_mfma_f32_16x16x32_bf16 v[6:9], v[192:195], v[232:235], v[6:9]
	v_mfma_f32_16x16x32_bf16 v[46:49], v[196:199], v[204:207], v[46:49]
	v_mfma_f32_16x16x32_bf16 v[46:49], v[200:203], v[208:211], v[46:49]
	v_mfma_f32_16x16x32_bf16 v[30:33], v[196:199], v[212:215], v[30:33]
	v_mfma_f32_16x16x32_bf16 v[30:33], v[200:203], v[216:219], v[30:33]
	v_mfma_f32_16x16x32_bf16 v[14:17], v[196:199], v[220:223], v[14:17]
	v_mfma_f32_16x16x32_bf16 v[14:17], v[200:203], v[224:227], v[14:17]
	v_mfma_f32_16x16x32_bf16 v[2:5], v[196:199], v[228:231], v[2:5]
	v_mfma_f32_16x16x32_bf16 v[2:5], v[200:203], v[232:235], v[2:5]
	s_setprio 0
	s_barrier
	s_add_i32 s87, s87, 2
	s_add_u32 s6, s6, 0x100
	s_addc_u32 s7, s7, 0
	s_add_u32 s85, s85, 0x100
	s_addc_u32 s86, s86, 0
	s_cmp_gt_u32 s87, 61
	s_cbranch_scc0 .LBB0_2464
	s_and_b64 vcc, exec, s[38:39]
	s_cbranch_vccz .LBB0_2467
	s_barrier

.LBB0_2494:
	ds_read_b128 v[160:163], v155
	ds_read_b128 v[164:167], v155 offset:1024
	ds_read_b128 v[168:171], v155 offset:2048
	ds_read_b128 v[172:175], v155 offset:3072
	ds_read_b128 v[176:179], v156
	ds_read_b128 v[184:187], v156 offset:1024
	ds_read_b128 v[188:191], v156 offset:2048
	ds_read_b128 v[192:195], v156 offset:3072
	s_add_u32 s48, s6, 0xfff00080
	s_addc_u32 s49, s7, -1
	s_cmp_eq_u32 s89, 60
	s_cselect_b32 s51, s43, s49
	s_cselect_b32 s50, s85, s48
	s_cselect_b32 s49, s41, s88
	s_cselect_b32 s48, s86, s87
	s_add_i32 m0, s63, 0xc000
	ds_read_b128 v[196:199], v157
	ds_read_b128 v[200:203], v157 offset:1024
	ds_read_b128 v[204:207], v157 offset:2048
	ds_read_b128 v[208:211], v157 offset:3072
	ds_read_b128 v[212:215], v157 offset:4096
	ds_read_b128 v[216:219], v157 offset:5120
	ds_read_b128 v[220:223], v157 offset:6144
	ds_read_b128 v[224:227], v157 offset:7168
	global_load_lds_dwordx4 v140, s[6:7]
	s_add_i32 m0, s63, 0xe000
	s_nop 0
	global_load_lds_dwordx4 v142, s[6:7]
	s_waitcnt vmcnt(8)
	s_waitcnt lgkmcnt(0)
	s_barrier
	s_setprio 1
	v_mfma_f32_16x16x32_bf16 v[126:129], v[160:163], v[196:199], v[126:129]
	v_mfma_f32_16x16x32_bf16 v[126:129], v[164:167], v[200:203], v[126:129]
	v_mfma_f32_16x16x32_bf16 v[110:113], v[160:163], v[204:207], v[110:113]
	v_mfma_f32_16x16x32_bf16 v[110:113], v[164:167], v[208:211], v[110:113]
	v_mfma_f32_16x16x32_bf16 v[94:97], v[160:163], v[212:215], v[94:97]
	v_mfma_f32_16x16x32_bf16 v[94:97], v[164:167], v[216:219], v[94:97]
	v_mfma_f32_16x16x32_bf16 v[78:81], v[160:163], v[220:223], v[78:81]
	v_mfma_f32_16x16x32_bf16 v[78:81], v[164:167], v[224:227], v[78:81]
	v_mfma_f32_16x16x32_bf16 v[122:125], v[168:171], v[196:199], v[122:125]
	v_mfma_f32_16x16x32_bf16 v[122:125], v[172:175], v[200:203], v[122:125]
	v_mfma_f32_16x16x32_bf16 v[106:109], v[168:171], v[204:207], v[106:109]
	v_mfma_f32_16x16x32_bf16 v[106:109], v[172:175], v[208:211], v[106:109]
	v_mfma_f32_16x16x32_bf16 v[90:93], v[168:171], v[212:215], v[90:93]
	v_mfma_f32_16x16x32_bf16 v[90:93], v[172:175], v[216:219], v[90:93]
	v_mfma_f32_16x16x32_bf16 v[74:77], v[168:171], v[220:223], v[74:77]
	v_mfma_f32_16x16x32_bf16 v[74:77], v[172:175], v[224:227], v[74:77]
	v_mfma_f32_16x16x32_bf16 v[118:121], v[176:179], v[196:199], v[118:121]
	v_mfma_f32_16x16x32_bf16 v[118:121], v[184:187], v[200:203], v[118:121]
	v_mfma_f32_16x16x32_bf16 v[102:105], v[176:179], v[204:207], v[102:105]
	v_mfma_f32_16x16x32_bf16 v[102:105], v[184:187], v[208:211], v[102:105]
	v_mfma_f32_16x16x32_bf16 v[86:89], v[176:179], v[212:215], v[86:89]
	v_mfma_f32_16x16x32_bf16 v[86:89], v[184:187], v[216:219], v[86:89]
	v_mfma_f32_16x16x32_bf16 v[70:73], v[176:179], v[220:223], v[70:73]
	v_mfma_f32_16x16x32_bf16 v[70:73], v[184:187], v[224:227], v[70:73]
	v_mfma_f32_16x16x32_bf16 v[114:117], v[188:191], v[196:199], v[114:117]
	v_mfma_f32_16x16x32_bf16 v[114:117], v[192:195], v[200:203], v[114:117]
	v_mfma_f32_16x16x32_bf16 v[98:101], v[188:191], v[204:207], v[98:101]
	v_mfma_f32_16x16x32_bf16 v[98:101], v[192:195], v[208:211], v[98:101]
	v_mfma_f32_16x16x32_bf16 v[82:85], v[188:191], v[212:215], v[82:85]
	v_mfma_f32_16x16x32_bf16 v[82:85], v[192:195], v[216:219], v[82:85]
	v_mfma_f32_16x16x32_bf16 v[66:69], v[188:191], v[220:223], v[66:69]
	v_mfma_f32_16x16x32_bf16 v[66:69], v[192:195], v[224:227], v[66:69]
	s_setprio 0
	s_barrier
	s_add_i32 s90, s73, s27
	s_add_u32 s98, s48, 0x80
	s_addc_u32 s99, s49, 0
	s_mov_b32 m0, s90
	ds_read_b128 v[196:199], v157 offset:16384
	ds_read_b128 v[200:203], v157 offset:17408
	ds_read_b128 v[204:207], v157 offset:18432
	ds_read_b128 v[208:211], v157 offset:19456
	ds_read_b128 v[212:215], v157 offset:20480
	ds_read_b128 v[216:219], v157 offset:21504
	ds_read_b128 v[220:223], v157 offset:22528
	ds_read_b128 v[224:227], v157 offset:23552
	global_load_lds_dwordx4 v132, s[48:49]
	s_add_i32 m0, s90, 0x2000
	s_add_u32 s90, s48, 0x100000
	s_addc_u32 s91, s49, 0
	s_add_i32 s92, s74, s27
	global_load_lds_dwordx4 v136, s[48:49]
	s_mov_b32 m0, s92
	global_load_lds_dwordx4 v132, s[90:91]
	s_add_i32 m0, s92, 0x2000
	s_nop 0
	global_load_lds_dwordx4 v136, s[90:91]
	s_add_u32 s100, s50, 0x80
	s_addc_u32 s101, s51, 0
	s_mov_b32 m0, s63
	s_nop 0
	global_load_lds_dwordx4 v130, s[50:51]
	s_mov_b32 m0, s65
	s_nop 0
	global_load_lds_dwordx4 v134, s[50:51]
	s_waitcnt vmcnt(8)
	s_waitcnt lgkmcnt(0)
	s_barrier
	s_setprio 1
	v_mfma_f32_16x16x32_bf16 v[62:65], v[160:163], v[196:199], v[62:65]
	v_mfma_f32_16x16x32_bf16 v[62:65], v[164:167], v[200:203], v[62:65]
	v_mfma_f32_16x16x32_bf16 v[50:53], v[160:163], v[204:207], v[50:53]
	v_mfma_f32_16x16x32_bf16 v[50:53], v[164:167], v[208:211], v[50:53]
	v_mfma_f32_16x16x32_bf16 v[34:37], v[160:163], v[212:215], v[34:37]
	v_mfma_f32_16x16x32_bf16 v[34:37], v[164:167], v[216:219], v[34:37]
	v_mfma_f32_16x16x32_bf16 v[18:21], v[160:163], v[220:223], v[18:21]
	v_mfma_f32_16x16x32_bf16 v[18:21], v[164:167], v[224:227], v[18:21]
	v_mfma_f32_16x16x32_bf16 v[58:61], v[168:171], v[196:199], v[58:61]
	v_mfma_f32_16x16x32_bf16 v[58:61], v[172:175], v[200:203], v[58:61]
	v_mfma_f32_16x16x32_bf16 v[42:45], v[168:171], v[204:207], v[42:45]
	v_mfma_f32_16x16x32_bf16 v[42:45], v[172:175], v[208:211], v[42:45]
	v_mfma_f32_16x16x32_bf16 v[26:29], v[168:171], v[212:215], v[26:29]
	v_mfma_f32_16x16x32_bf16 v[26:29], v[172:175], v[216:219], v[26:29]
	v_mfma_f32_16x16x32_bf16 v[10:13], v[168:171], v[220:223], v[10:13]
	v_mfma_f32_16x16x32_bf16 v[10:13], v[172:175], v[224:227], v[10:13]
	v_mfma_f32_16x16x32_bf16 v[54:57], v[176:179], v[196:199], v[54:57]
	v_mfma_f32_16x16x32_bf16 v[54:57], v[184:187], v[200:203], v[54:57]
	v_mfma_f32_16x16x32_bf16 v[38:41], v[176:179], v[204:207], v[38:41]
	v_mfma_f32_16x16x32_bf16 v[38:41], v[184:187], v[208:211], v[38:41]
	v_mfma_f32_16x16x32_bf16 v[22:25], v[176:179], v[212:215], v[22:25]
	v_mfma_f32_16x16x32_bf16 v[22:25], v[184:187], v[216:219], v[22:25]
	v_mfma_f32_16x16x32_bf16 v[6:9], v[176:179], v[220:223], v[6:9]
	v_mfma_f32_16x16x32_bf16 v[6:9], v[184:187], v[224:227], v[6:9]
	v_mfma_f32_16x16x32_bf16 v[46:49], v[188:191], v[196:199], v[46:49]
	v_mfma_f32_16x16x32_bf16 v[46:49], v[192:195], v[200:203], v[46:49]
	v_mfma_f32_16x16x32_bf16 v[30:33], v[188:191], v[204:207], v[30:33]
	v_mfma_f32_16x16x32_bf16 v[30:33], v[192:195], v[208:211], v[30:33]
	v_mfma_f32_16x16x32_bf16 v[14:17], v[188:191], v[212:215], v[14:17]
	v_mfma_f32_16x16x32_bf16 v[14:17], v[192:195], v[216:219], v[14:17]
	v_mfma_f32_16x16x32_bf16 v[2:5], v[188:191], v[220:223], v[2:5]
	v_mfma_f32_16x16x32_bf16 v[2:5], v[192:195], v[224:227], v[2:5]
	s_setprio 0
	s_barrier
	s_add_i32 s90, 0, 0x18000
	v_add_u32_e32 v138, s90, v151
	s_add_i32 s91, 0, 0x1c000
	ds_read_b128 v[160:163], v138
	ds_read_b128 v[164:167], v138 offset:1024
	ds_read_b128 v[168:171], v138 offset:2048
	ds_read_b128 v[172:175], v138 offset:3072
	v_add_u32_e32 v138, s91, v151
	ds_read_b128 v[176:179], v138
	ds_read_b128 v[184:187], v138 offset:1024
	ds_read_b128 v[188:191], v138 offset:2048
	ds_read_b128 v[192:195], v138 offset:3072
	s_add_u32 s50, s50, 0x100000
	s_addc_u32 s51, s51, 0
	s_mov_b32 m0, s66
	ds_read_b128 v[196:199], v157 offset:32768
	ds_read_b128 v[200:203], v157 offset:33792
	ds_read_b128 v[204:207], v157 offset:34816
	ds_read_b128 v[208:211], v157 offset:35840
	ds_read_b128 v[212:215], v157 offset:36864
	ds_read_b128 v[216:219], v157 offset:37888
	ds_read_b128 v[220:223], v157 offset:38912
	ds_read_b128 v[224:227], v157 offset:39936
	global_load_lds_dwordx4 v130, s[50:51]
	s_mov_b32 m0, s67
	s_nop 0
	global_load_lds_dwordx4 v134, s[50:51]
	s_waitcnt vmcnt(8)
	s_waitcnt lgkmcnt(0)
	s_barrier
	s_setprio 1
	v_mfma_f32_16x16x32_bf16 v[126:129], v[160:163], v[196:199], v[126:129]
	v_mfma_f32_16x16x32_bf16 v[126:129], v[164:167], v[200:203], v[126:129]
	v_mfma_f32_16x16x32_bf16 v[110:113], v[160:163], v[204:207], v[110:113]
	v_mfma_f32_16x16x32_bf16 v[110:113], v[164:167], v[208:211], v[110:113]
	v_mfma_f32_16x16x32_bf16 v[94:97], v[160:163], v[212:215], v[94:97]
	v_mfma_f32_16x16x32_bf16 v[94:97], v[164:167], v[216:219], v[94:97]
	v_mfma_f32_16x16x32_bf16 v[78:81], v[160:163], v[220:223], v[78:81]
	v_mfma_f32_16x16x32_bf16 v[78:81], v[164:167], v[224:227], v[78:81]
	v_mfma_f32_16x16x32_bf16 v[122:125], v[168:171], v[196:199], v[122:125]
	v_mfma_f32_16x16x32_bf16 v[122:125], v[172:175], v[200:203], v[122:125]
	v_mfma_f32_16x16x32_bf16 v[106:109], v[168:171], v[204:207], v[106:109]
	v_mfma_f32_16x16x32_bf16 v[106:109], v[172:175], v[208:211], v[106:109]
	v_mfma_f32_16x16x32_bf16 v[90:93], v[168:171], v[212:215], v[90:93]
	v_mfma_f32_16x16x32_bf16 v[90:93], v[172:175], v[216:219], v[90:93]
	v_mfma_f32_16x16x32_bf16 v[74:77], v[168:171], v[220:223], v[74:77]
	v_mfma_f32_16x16x32_bf16 v[74:77], v[172:175], v[224:227], v[74:77]
	v_mfma_f32_16x16x32_bf16 v[118:121], v[176:179], v[196:199], v[118:121]
	v_mfma_f32_16x16x32_bf16 v[118:121], v[184:187], v[200:203], v[118:121]
	v_mfma_f32_16x16x32_bf16 v[102:105], v[176:179], v[204:207], v[102:105]
	v_mfma_f32_16x16x32_bf16 v[102:105], v[184:187], v[208:211], v[102:105]
	v_mfma_f32_16x16x32_bf16 v[86:89], v[176:179], v[212:215], v[86:89]
	v_mfma_f32_16x16x32_bf16 v[86:89], v[184:187], v[216:219], v[86:89]
	v_mfma_f32_16x16x32_bf16 v[70:73], v[176:179], v[220:223], v[70:73]
	v_mfma_f32_16x16x32_bf16 v[70:73], v[184:187], v[224:227], v[70:73]
	v_mfma_f32_16x16x32_bf16 v[114:117], v[188:191], v[196:199], v[114:117]
	v_mfma_f32_16x16x32_bf16 v[114:117], v[192:195], v[200:203], v[114:117]
	v_mfma_f32_16x16x32_bf16 v[98:101], v[188:191], v[204:207], v[98:101]
	v_mfma_f32_16x16x32_bf16 v[98:101], v[192:195], v[208:211], v[98:101]
	v_mfma_f32_16x16x32_bf16 v[82:85], v[188:191], v[212:215], v[82:85]
	v_mfma_f32_16x16x32_bf16 v[82:85], v[192:195], v[216:219], v[82:85]
	v_mfma_f32_16x16x32_bf16 v[66:69], v[188:191], v[220:223], v[66:69]
	v_mfma_f32_16x16x32_bf16 v[66:69], v[192:195], v[224:227], v[66:69]
	s_setprio 0
	s_barrier
	s_add_i32 s50, s90, s27
	s_mov_b32 m0, s50
	ds_read_b128 v[196:199], v157 offset:49152
	ds_read_b128 v[200:203], v157 offset:50176
	ds_read_b128 v[204:207], v157 offset:51200
	ds_read_b128 v[208:211], v157 offset:52224
	ds_read_b128 v[212:215], v157 offset:53248
	ds_read_b128 v[216:219], v157 offset:54272
	ds_read_b128 v[220:223], v157 offset:55296
	ds_read_b128 v[224:227], v157 offset:56320
	global_load_lds_dwordx4 v132, s[98:99]
	s_add_i32 m0, s50, 0x2000
	s_add_u32 s48, s48, 0x100080
	s_addc_u32 s49, s49, 0
	s_add_i32 s50, s91, s27
	global_load_lds_dwordx4 v136, s[98:99]
	s_mov_b32 m0, s50
	s_nop 0
	global_load_lds_dwordx4 v132, s[48:49]
	s_add_i32 m0, s50, 0x2000
	s_nop 0
	global_load_lds_dwordx4 v136, s[48:49]
	s_mov_b32 m0, s69
	s_nop 0
	global_load_lds_dwordx4 v130, s[100:101]
	s_mov_b32 m0, s70
	s_nop 0
	global_load_lds_dwordx4 v134, s[100:101]
	s_waitcnt vmcnt(8)
	s_waitcnt lgkmcnt(0)
	s_barrier
	s_setprio 1
	v_mfma_f32_16x16x32_bf16 v[62:65], v[160:163], v[196:199], v[62:65]
	v_mfma_f32_16x16x32_bf16 v[62:65], v[164:167], v[200:203], v[62:65]
	v_mfma_f32_16x16x32_bf16 v[50:53], v[160:163], v[204:207], v[50:53]
	v_mfma_f32_16x16x32_bf16 v[50:53], v[164:167], v[208:211], v[50:53]
	v_mfma_f32_16x16x32_bf16 v[34:37], v[160:163], v[212:215], v[34:37]
	v_mfma_f32_16x16x32_bf16 v[34:37], v[164:167], v[216:219], v[34:37]
	v_mfma_f32_16x16x32_bf16 v[18:21], v[160:163], v[220:223], v[18:21]
	v_mfma_f32_16x16x32_bf16 v[18:21], v[164:167], v[224:227], v[18:21]
	v_mfma_f32_16x16x32_bf16 v[58:61], v[168:171], v[196:199], v[58:61]
	v_mfma_f32_16x16x32_bf16 v[58:61], v[172:175], v[200:203], v[58:61]
	v_mfma_f32_16x16x32_bf16 v[42:45], v[168:171], v[204:207], v[42:45]
	v_mfma_f32_16x16x32_bf16 v[42:45], v[172:175], v[208:211], v[42:45]
	v_mfma_f32_16x16x32_bf16 v[26:29], v[168:171], v[212:215], v[26:29]
	v_mfma_f32_16x16x32_bf16 v[26:29], v[172:175], v[216:219], v[26:29]
	v_mfma_f32_16x16x32_bf16 v[10:13], v[168:171], v[220:223], v[10:13]
	v_mfma_f32_16x16x32_bf16 v[10:13], v[172:175], v[224:227], v[10:13]
	v_mfma_f32_16x16x32_bf16 v[54:57], v[176:179], v[196:199], v[54:57]
	v_mfma_f32_16x16x32_bf16 v[54:57], v[184:187], v[200:203], v[54:57]
	v_mfma_f32_16x16x32_bf16 v[38:41], v[176:179], v[204:207], v[38:41]
	v_mfma_f32_16x16x32_bf16 v[38:41], v[184:187], v[208:211], v[38:41]
	v_mfma_f32_16x16x32_bf16 v[22:25], v[176:179], v[212:215], v[22:25]
	v_mfma_f32_16x16x32_bf16 v[22:25], v[184:187], v[216:219], v[22:25]
	v_mfma_f32_16x16x32_bf16 v[6:9], v[176:179], v[220:223], v[6:9]
	v_mfma_f32_16x16x32_bf16 v[6:9], v[184:187], v[224:227], v[6:9]
	v_mfma_f32_16x16x32_bf16 v[46:49], v[188:191], v[196:199], v[46:49]
	v_mfma_f32_16x16x32_bf16 v[46:49], v[192:195], v[200:203], v[46:49]
	v_mfma_f32_16x16x32_bf16 v[30:33], v[188:191], v[204:207], v[30:33]
	v_mfma_f32_16x16x32_bf16 v[30:33], v[192:195], v[208:211], v[30:33]
	v_mfma_f32_16x16x32_bf16 v[14:17], v[188:191], v[212:215], v[14:17]
	v_mfma_f32_16x16x32_bf16 v[14:17], v[192:195], v[216:219], v[14:17]
	v_mfma_f32_16x16x32_bf16 v[2:5], v[188:191], v[220:223], v[2:5]
	v_mfma_f32_16x16x32_bf16 v[2:5], v[192:195], v[224:227], v[2:5]
	s_setprio 0
	s_barrier
	s_add_i32 s89, s89, 2
	s_add_u32 s6, s6, 0x100
	s_addc_u32 s7, s7, 0
	s_add_u32 s87, s87, 0x100
	s_addc_u32 s88, s88, 0
	s_cmp_gt_u32 s89, 61
	s_cbranch_scc0 .LBB0_2494
	s_and_b64 vcc, exec, s[38:39]
	s_cbranch_vccz .LBB0_2497
	s_barrier

.LBB0_2635:
	ds_read_b128 v[130:133], v163
	ds_read_b128 v[134:137], v163 offset:1024
	ds_read_b128 v[138:141], v163 offset:2048
	ds_read_b128 v[142:145], v163 offset:3072
	ds_read_b128 v[146:149], v188
	ds_read_b128 v[150:153], v188 offset:1024
	ds_read_b128 v[174:177], v188 offset:2048
	ds_read_b128 v[178:181], v188 offset:3072
	s_add_u32 s48, s46, 0xfff00080
	s_addc_u32 s49, s47, -1
	s_cmp_eq_u32 s73, 60
	s_cselect_b32 s51, s22, s49
	s_cselect_b32 s50, s41, s48
	s_cselect_b32 s49, s39, s72
	s_cselect_b32 s48, s70, s71
	s_add_i32 m0, s13, 0xc000
	ds_read_b128 v[184:187], v189
	ds_read_b128 v[192:195], v189 offset:1024
	ds_read_b128 v[196:199], v189 offset:2048
	ds_read_b128 v[200:203], v189 offset:3072
	ds_read_b128 v[204:207], v189 offset:4096
	ds_read_b128 v[208:211], v189 offset:5120
	ds_read_b128 v[212:215], v189 offset:6144
	ds_read_b128 v[216:219], v189 offset:7168
	global_load_lds_dwordx4 v166, s[46:47]
	s_add_i32 m0, s13, 0xe000
	s_nop 0
	global_load_lds_dwordx4 v168, s[46:47]
	s_waitcnt vmcnt(8)
	s_waitcnt lgkmcnt(0)
	s_barrier
	s_setprio 1
	v_mfma_f32_16x16x32_bf16 v[126:129], v[130:133], v[184:187], v[126:129]
	v_mfma_f32_16x16x32_bf16 v[126:129], v[134:137], v[192:195], v[126:129]
	v_mfma_f32_16x16x32_bf16 v[110:113], v[130:133], v[196:199], v[110:113]
	v_mfma_f32_16x16x32_bf16 v[110:113], v[134:137], v[200:203], v[110:113]
	v_mfma_f32_16x16x32_bf16 v[94:97], v[130:133], v[204:207], v[94:97]
	v_mfma_f32_16x16x32_bf16 v[94:97], v[134:137], v[208:211], v[94:97]
	v_mfma_f32_16x16x32_bf16 v[78:81], v[130:133], v[212:215], v[78:81]
	v_mfma_f32_16x16x32_bf16 v[78:81], v[134:137], v[216:219], v[78:81]
	v_mfma_f32_16x16x32_bf16 v[122:125], v[138:141], v[184:187], v[122:125]
	v_mfma_f32_16x16x32_bf16 v[122:125], v[142:145], v[192:195], v[122:125]
	v_mfma_f32_16x16x32_bf16 v[106:109], v[138:141], v[196:199], v[106:109]
	v_mfma_f32_16x16x32_bf16 v[106:109], v[142:145], v[200:203], v[106:109]
	v_mfma_f32_16x16x32_bf16 v[90:93], v[138:141], v[204:207], v[90:93]
	v_mfma_f32_16x16x32_bf16 v[90:93], v[142:145], v[208:211], v[90:93]
	v_mfma_f32_16x16x32_bf16 v[74:77], v[138:141], v[212:215], v[74:77]
	v_mfma_f32_16x16x32_bf16 v[74:77], v[142:145], v[216:219], v[74:77]
	v_mfma_f32_16x16x32_bf16 v[118:121], v[146:149], v[184:187], v[118:121]
	v_mfma_f32_16x16x32_bf16 v[118:121], v[150:153], v[192:195], v[118:121]
	v_mfma_f32_16x16x32_bf16 v[102:105], v[146:149], v[196:199], v[102:105]
	v_mfma_f32_16x16x32_bf16 v[102:105], v[150:153], v[200:203], v[102:105]
	v_mfma_f32_16x16x32_bf16 v[86:89], v[146:149], v[204:207], v[86:89]
	v_mfma_f32_16x16x32_bf16 v[86:89], v[150:153], v[208:211], v[86:89]
	v_mfma_f32_16x16x32_bf16 v[70:73], v[146:149], v[212:215], v[70:73]
	v_mfma_f32_16x16x32_bf16 v[70:73], v[150:153], v[216:219], v[70:73]
	v_mfma_f32_16x16x32_bf16 v[114:117], v[174:177], v[184:187], v[114:117]
	v_mfma_f32_16x16x32_bf16 v[114:117], v[178:181], v[192:195], v[114:117]
	v_mfma_f32_16x16x32_bf16 v[98:101], v[174:177], v[196:199], v[98:101]
	v_mfma_f32_16x16x32_bf16 v[98:101], v[178:181], v[200:203], v[98:101]
	v_mfma_f32_16x16x32_bf16 v[82:85], v[174:177], v[204:207], v[82:85]
	v_mfma_f32_16x16x32_bf16 v[82:85], v[178:181], v[208:211], v[82:85]
	v_mfma_f32_16x16x32_bf16 v[66:69], v[174:177], v[212:215], v[66:69]
	v_mfma_f32_16x16x32_bf16 v[66:69], v[178:181], v[216:219], v[66:69]
	s_setprio 0
	s_barrier
	s_add_i32 s74, s67, s3
	s_add_u32 s98, s48, 0x80
	s_addc_u32 s99, s49, 0
	s_mov_b32 m0, s74
	ds_read_b128 v[184:187], v189 offset:16384
	ds_read_b128 v[192:195], v189 offset:17408
	ds_read_b128 v[196:199], v189 offset:18432
	ds_read_b128 v[200:203], v189 offset:19456
	ds_read_b128 v[204:207], v189 offset:20480
	ds_read_b128 v[208:211], v189 offset:21504
	ds_read_b128 v[212:215], v189 offset:22528
	ds_read_b128 v[216:219], v189 offset:23552
	global_load_lds_dwordx4 v156, s[48:49]
	s_add_i32 m0, s74, 0x2000
	s_add_u32 s74, s48, 0x100000
	s_addc_u32 s75, s49, 0
	s_add_i32 s76, s68, s3
	global_load_lds_dwordx4 v160, s[48:49]
	s_mov_b32 m0, s76
	global_load_lds_dwordx4 v156, s[74:75]
	s_add_i32 m0, s76, 0x2000
	s_nop 0
	global_load_lds_dwordx4 v160, s[74:75]
	s_add_u32 s100, s50, 0x80
	s_addc_u32 s101, s51, 0
	s_mov_b32 m0, s13
	s_nop 0
	global_load_lds_dwordx4 v154, s[50:51]
	s_mov_b32 m0, s21
	s_nop 0
	global_load_lds_dwordx4 v158, s[50:51]
	s_waitcnt vmcnt(8)
	s_waitcnt lgkmcnt(0)
	s_barrier
	s_setprio 1
	v_mfma_f32_16x16x32_bf16 v[62:65], v[130:133], v[184:187], v[62:65]
	v_mfma_f32_16x16x32_bf16 v[62:65], v[134:137], v[192:195], v[62:65]
	v_mfma_f32_16x16x32_bf16 v[46:49], v[130:133], v[196:199], v[46:49]
	v_mfma_f32_16x16x32_bf16 v[46:49], v[134:137], v[200:203], v[46:49]
	v_mfma_f32_16x16x32_bf16 v[30:33], v[130:133], v[204:207], v[30:33]
	v_mfma_f32_16x16x32_bf16 v[30:33], v[134:137], v[208:211], v[30:33]
	v_mfma_f32_16x16x32_bf16 v[14:17], v[130:133], v[212:215], v[14:17]
	v_mfma_f32_16x16x32_bf16 v[14:17], v[134:137], v[216:219], v[14:17]
	v_mfma_f32_16x16x32_bf16 v[58:61], v[138:141], v[184:187], v[58:61]
	v_mfma_f32_16x16x32_bf16 v[58:61], v[142:145], v[192:195], v[58:61]
	v_mfma_f32_16x16x32_bf16 v[42:45], v[138:141], v[196:199], v[42:45]
	v_mfma_f32_16x16x32_bf16 v[42:45], v[142:145], v[200:203], v[42:45]
	v_mfma_f32_16x16x32_bf16 v[26:29], v[138:141], v[204:207], v[26:29]
	v_mfma_f32_16x16x32_bf16 v[26:29], v[142:145], v[208:211], v[26:29]
	v_mfma_f32_16x16x32_bf16 v[10:13], v[138:141], v[212:215], v[10:13]
	v_mfma_f32_16x16x32_bf16 v[10:13], v[142:145], v[216:219], v[10:13]
	v_mfma_f32_16x16x32_bf16 v[54:57], v[146:149], v[184:187], v[54:57]
	v_mfma_f32_16x16x32_bf16 v[54:57], v[150:153], v[192:195], v[54:57]
	v_mfma_f32_16x16x32_bf16 v[38:41], v[146:149], v[196:199], v[38:41]
	v_mfma_f32_16x16x32_bf16 v[38:41], v[150:153], v[200:203], v[38:41]
	v_mfma_f32_16x16x32_bf16 v[22:25], v[146:149], v[204:207], v[22:25]
	v_mfma_f32_16x16x32_bf16 v[22:25], v[150:153], v[208:211], v[22:25]
	v_mfma_f32_16x16x32_bf16 v[6:9], v[146:149], v[212:215], v[6:9]
	v_mfma_f32_16x16x32_bf16 v[6:9], v[150:153], v[216:219], v[6:9]
	v_mfma_f32_16x16x32_bf16 v[50:53], v[174:177], v[184:187], v[50:53]
	v_mfma_f32_16x16x32_bf16 v[50:53], v[178:181], v[192:195], v[50:53]
	v_mfma_f32_16x16x32_bf16 v[34:37], v[174:177], v[196:199], v[34:37]
	v_mfma_f32_16x16x32_bf16 v[34:37], v[178:181], v[200:203], v[34:37]
	v_mfma_f32_16x16x32_bf16 v[18:21], v[174:177], v[204:207], v[18:21]
	v_mfma_f32_16x16x32_bf16 v[18:21], v[178:181], v[208:211], v[18:21]
	v_mfma_f32_16x16x32_bf16 v[2:5], v[174:177], v[212:215], v[2:5]
	v_mfma_f32_16x16x32_bf16 v[2:5], v[178:181], v[216:219], v[2:5]
	s_setprio 0
	s_barrier
	s_add_i32 s74, 0, 0x18000
	s_add_i32 s75, 0, 0x1c000
	v_add_u32_e32 v142, s74, v1
	v_add_u32_e32 v178, s75, v1
	ds_read_b128 v[130:133], v142
	ds_read_b128 v[134:137], v142 offset:1024
	ds_read_b128 v[138:141], v142 offset:2048
	ds_read_b128 v[142:145], v142 offset:3072
	ds_read_b128 v[146:149], v178
	ds_read_b128 v[150:153], v178 offset:1024
	ds_read_b128 v[174:177], v178 offset:2048
	ds_read_b128 v[178:181], v178 offset:3072
	s_add_u32 s50, s50, 0x100000
	s_addc_u32 s51, s51, 0
	s_mov_b32 m0, s33
	ds_read_b128 v[184:187], v189 offset:32768
	ds_read_b128 v[192:195], v189 offset:33792
	ds_read_b128 v[196:199], v189 offset:34816
	ds_read_b128 v[200:203], v189 offset:35840
	ds_read_b128 v[204:207], v189 offset:36864
	ds_read_b128 v[208:211], v189 offset:37888
	ds_read_b128 v[212:215], v189 offset:38912
	ds_read_b128 v[216:219], v189 offset:39936
	global_load_lds_dwordx4 v154, s[50:51]
	s_mov_b32 m0, s35
	s_nop 0
	global_load_lds_dwordx4 v158, s[50:51]
	s_waitcnt vmcnt(8)
	s_waitcnt lgkmcnt(0)
	s_barrier
	s_setprio 1
	v_mfma_f32_16x16x32_bf16 v[126:129], v[130:133], v[184:187], v[126:129]
	v_mfma_f32_16x16x32_bf16 v[126:129], v[134:137], v[192:195], v[126:129]
	v_mfma_f32_16x16x32_bf16 v[110:113], v[130:133], v[196:199], v[110:113]
	v_mfma_f32_16x16x32_bf16 v[110:113], v[134:137], v[200:203], v[110:113]
	v_mfma_f32_16x16x32_bf16 v[94:97], v[130:133], v[204:207], v[94:97]
	v_mfma_f32_16x16x32_bf16 v[94:97], v[134:137], v[208:211], v[94:97]
	v_mfma_f32_16x16x32_bf16 v[78:81], v[130:133], v[212:215], v[78:81]
	v_mfma_f32_16x16x32_bf16 v[78:81], v[134:137], v[216:219], v[78:81]
	v_mfma_f32_16x16x32_bf16 v[122:125], v[138:141], v[184:187], v[122:125]
	v_mfma_f32_16x16x32_bf16 v[122:125], v[142:145], v[192:195], v[122:125]
	v_mfma_f32_16x16x32_bf16 v[106:109], v[138:141], v[196:199], v[106:109]
	v_mfma_f32_16x16x32_bf16 v[106:109], v[142:145], v[200:203], v[106:109]
	v_mfma_f32_16x16x32_bf16 v[90:93], v[138:141], v[204:207], v[90:93]
	v_mfma_f32_16x16x32_bf16 v[90:93], v[142:145], v[208:211], v[90:93]
	v_mfma_f32_16x16x32_bf16 v[74:77], v[138:141], v[212:215], v[74:77]
	v_mfma_f32_16x16x32_bf16 v[74:77], v[142:145], v[216:219], v[74:77]
	v_mfma_f32_16x16x32_bf16 v[118:121], v[146:149], v[184:187], v[118:121]
	v_mfma_f32_16x16x32_bf16 v[118:121], v[150:153], v[192:195], v[118:121]
	v_mfma_f32_16x16x32_bf16 v[102:105], v[146:149], v[196:199], v[102:105]
	v_mfma_f32_16x16x32_bf16 v[102:105], v[150:153], v[200:203], v[102:105]
	v_mfma_f32_16x16x32_bf16 v[86:89], v[146:149], v[204:207], v[86:89]
	v_mfma_f32_16x16x32_bf16 v[86:89], v[150:153], v[208:211], v[86:89]
	v_mfma_f32_16x16x32_bf16 v[70:73], v[146:149], v[212:215], v[70:73]
	v_mfma_f32_16x16x32_bf16 v[70:73], v[150:153], v[216:219], v[70:73]
	v_mfma_f32_16x16x32_bf16 v[114:117], v[174:177], v[184:187], v[114:117]
	v_mfma_f32_16x16x32_bf16 v[114:117], v[178:181], v[192:195], v[114:117]
	v_mfma_f32_16x16x32_bf16 v[98:101], v[174:177], v[196:199], v[98:101]
	v_mfma_f32_16x16x32_bf16 v[98:101], v[178:181], v[200:203], v[98:101]
	v_mfma_f32_16x16x32_bf16 v[82:85], v[174:177], v[204:207], v[82:85]
	v_mfma_f32_16x16x32_bf16 v[82:85], v[178:181], v[208:211], v[82:85]
	v_mfma_f32_16x16x32_bf16 v[66:69], v[174:177], v[212:215], v[66:69]
	v_mfma_f32_16x16x32_bf16 v[66:69], v[178:181], v[216:219], v[66:69]
	s_setprio 0
	s_barrier
	s_add_i32 s50, s74, s3
	s_mov_b32 m0, s50
	ds_read_b128 v[184:187], v189 offset:49152
	ds_read_b128 v[192:195], v189 offset:50176
	ds_read_b128 v[196:199], v189 offset:51200
	ds_read_b128 v[200:203], v189 offset:52224
	ds_read_b128 v[204:207], v189 offset:53248
	ds_read_b128 v[208:211], v189 offset:54272
	ds_read_b128 v[212:215], v189 offset:55296
	ds_read_b128 v[216:219], v189 offset:56320
	global_load_lds_dwordx4 v156, s[98:99]
	s_add_i32 m0, s50, 0x2000
	s_add_u32 s48, s48, 0x100080
	s_addc_u32 s49, s49, 0
	s_add_i32 s50, s75, s3
	global_load_lds_dwordx4 v160, s[98:99]
	s_mov_b32 m0, s50
	s_nop 0
	global_load_lds_dwordx4 v156, s[48:49]
	s_add_i32 m0, s50, 0x2000
	s_nop 0
	global_load_lds_dwordx4 v160, s[48:49]
	s_mov_b32 m0, s62
	s_nop 0
	global_load_lds_dwordx4 v154, s[100:101]
	s_mov_b32 m0, s63
	s_nop 0
	global_load_lds_dwordx4 v158, s[100:101]
	s_waitcnt vmcnt(8)
	s_waitcnt lgkmcnt(0)
	s_barrier
	s_setprio 1
	v_mfma_f32_16x16x32_bf16 v[62:65], v[130:133], v[184:187], v[62:65]
	v_mfma_f32_16x16x32_bf16 v[62:65], v[134:137], v[192:195], v[62:65]
	v_mfma_f32_16x16x32_bf16 v[46:49], v[130:133], v[196:199], v[46:49]
	v_mfma_f32_16x16x32_bf16 v[46:49], v[134:137], v[200:203], v[46:49]
	v_mfma_f32_16x16x32_bf16 v[30:33], v[130:133], v[204:207], v[30:33]
	v_mfma_f32_16x16x32_bf16 v[30:33], v[134:137], v[208:211], v[30:33]
	v_mfma_f32_16x16x32_bf16 v[14:17], v[130:133], v[212:215], v[14:17]
	v_mfma_f32_16x16x32_bf16 v[14:17], v[134:137], v[216:219], v[14:17]
	v_mfma_f32_16x16x32_bf16 v[58:61], v[138:141], v[184:187], v[58:61]
	v_mfma_f32_16x16x32_bf16 v[58:61], v[142:145], v[192:195], v[58:61]
	v_mfma_f32_16x16x32_bf16 v[42:45], v[138:141], v[196:199], v[42:45]
	v_mfma_f32_16x16x32_bf16 v[42:45], v[142:145], v[200:203], v[42:45]
	v_mfma_f32_16x16x32_bf16 v[26:29], v[138:141], v[204:207], v[26:29]
	v_mfma_f32_16x16x32_bf16 v[26:29], v[142:145], v[208:211], v[26:29]
	v_mfma_f32_16x16x32_bf16 v[10:13], v[138:141], v[212:215], v[10:13]
	v_mfma_f32_16x16x32_bf16 v[10:13], v[142:145], v[216:219], v[10:13]
	v_mfma_f32_16x16x32_bf16 v[54:57], v[146:149], v[184:187], v[54:57]
	v_mfma_f32_16x16x32_bf16 v[54:57], v[150:153], v[192:195], v[54:57]
	v_mfma_f32_16x16x32_bf16 v[38:41], v[146:149], v[196:199], v[38:41]
	v_mfma_f32_16x16x32_bf16 v[38:41], v[150:153], v[200:203], v[38:41]
	v_mfma_f32_16x16x32_bf16 v[22:25], v[146:149], v[204:207], v[22:25]
	v_mfma_f32_16x16x32_bf16 v[22:25], v[150:153], v[208:211], v[22:25]
	v_mfma_f32_16x16x32_bf16 v[6:9], v[146:149], v[212:215], v[6:9]
	v_mfma_f32_16x16x32_bf16 v[6:9], v[150:153], v[216:219], v[6:9]
	v_mfma_f32_16x16x32_bf16 v[50:53], v[174:177], v[184:187], v[50:53]
	v_mfma_f32_16x16x32_bf16 v[50:53], v[178:181], v[192:195], v[50:53]
	v_mfma_f32_16x16x32_bf16 v[34:37], v[174:177], v[196:199], v[34:37]
	v_mfma_f32_16x16x32_bf16 v[34:37], v[178:181], v[200:203], v[34:37]
	v_mfma_f32_16x16x32_bf16 v[18:21], v[174:177], v[204:207], v[18:21]
	v_mfma_f32_16x16x32_bf16 v[18:21], v[178:181], v[208:211], v[18:21]
	v_mfma_f32_16x16x32_bf16 v[2:5], v[174:177], v[212:215], v[2:5]
	v_mfma_f32_16x16x32_bf16 v[2:5], v[178:181], v[216:219], v[2:5]
	s_setprio 0
	s_barrier
	s_add_i32 s73, s73, 2
	s_add_u32 s46, s46, 0x100
	s_addc_u32 s47, s47, 0
	s_add_u32 s71, s71, 0x100
	s_addc_u32 s72, s72, 0
	s_cmp_gt_u32 s73, 61
	s_cbranch_scc0 .LBB0_2635
	s_and_b64 vcc, exec, s[36:37]
	s_cbranch_vccz .LBB0_2638
	s_barrier

.LBB0_2720:
	ds_read_b128 v[148:151], v159
	ds_read_b128 v[164:167], v159 offset:1024
	ds_read_b128 v[168:171], v159 offset:2048
	ds_read_b128 v[172:175], v159 offset:3072
	ds_read_b128 v[176:179], v160
	ds_read_b128 v[184:187], v160 offset:1024
	ds_read_b128 v[188:191], v160 offset:2048
	ds_read_b128 v[192:195], v160 offset:3072
	s_add_u32 s40, s6, 0xfff00080
	s_addc_u32 s41, s7, -1
	s_cmp_eq_u32 s82, 60
	s_cselect_b32 s43, s29, s41
	s_cselect_b32 s42, s78, s40
	s_cselect_b32 s41, s27, s81
	s_cselect_b32 s40, s79, s80
	s_add_i32 m0, s44, 0xc000
	ds_read_b128 v[196:199], v161
	ds_read_b128 v[200:203], v161 offset:1024
	ds_read_b128 v[204:207], v161 offset:2048
	ds_read_b128 v[208:211], v161 offset:3072
	ds_read_b128 v[212:215], v161 offset:4096
	ds_read_b128 v[216:219], v161 offset:5120
	ds_read_b128 v[220:223], v161 offset:6144
	ds_read_b128 v[224:227], v161 offset:7168
	global_load_lds_dwordx4 v140, s[6:7]
	s_add_i32 m0, s44, 0xe000
	s_nop 0
	global_load_lds_dwordx4 v142, s[6:7]
	s_waitcnt vmcnt(8)
	s_waitcnt lgkmcnt(0)
	s_barrier
	s_setprio 1
	v_mfma_f32_16x16x32_bf16 v[126:129], v[148:151], v[196:199], v[126:129]
	v_mfma_f32_16x16x32_bf16 v[126:129], v[164:167], v[200:203], v[126:129]
	v_mfma_f32_16x16x32_bf16 v[110:113], v[148:151], v[204:207], v[110:113]
	v_mfma_f32_16x16x32_bf16 v[110:113], v[164:167], v[208:211], v[110:113]
	v_mfma_f32_16x16x32_bf16 v[94:97], v[148:151], v[212:215], v[94:97]
	v_mfma_f32_16x16x32_bf16 v[94:97], v[164:167], v[216:219], v[94:97]
	v_mfma_f32_16x16x32_bf16 v[78:81], v[148:151], v[220:223], v[78:81]
	v_mfma_f32_16x16x32_bf16 v[78:81], v[164:167], v[224:227], v[78:81]
	v_mfma_f32_16x16x32_bf16 v[118:121], v[168:171], v[196:199], v[118:121]
	v_mfma_f32_16x16x32_bf16 v[118:121], v[172:175], v[200:203], v[118:121]
	v_mfma_f32_16x16x32_bf16 v[102:105], v[168:171], v[204:207], v[102:105]
	v_mfma_f32_16x16x32_bf16 v[102:105], v[172:175], v[208:211], v[102:105]
	v_mfma_f32_16x16x32_bf16 v[86:89], v[168:171], v[212:215], v[86:89]
	v_mfma_f32_16x16x32_bf16 v[86:89], v[172:175], v[216:219], v[86:89]
	v_mfma_f32_16x16x32_bf16 v[70:73], v[168:171], v[220:223], v[70:73]
	v_mfma_f32_16x16x32_bf16 v[70:73], v[172:175], v[224:227], v[70:73]
	v_mfma_f32_16x16x32_bf16 v[122:125], v[176:179], v[196:199], v[122:125]
	v_mfma_f32_16x16x32_bf16 v[122:125], v[184:187], v[200:203], v[122:125]
	v_mfma_f32_16x16x32_bf16 v[106:109], v[176:179], v[204:207], v[106:109]
	v_mfma_f32_16x16x32_bf16 v[106:109], v[184:187], v[208:211], v[106:109]
	v_mfma_f32_16x16x32_bf16 v[90:93], v[176:179], v[212:215], v[90:93]
	v_mfma_f32_16x16x32_bf16 v[90:93], v[184:187], v[216:219], v[90:93]
	v_mfma_f32_16x16x32_bf16 v[74:77], v[176:179], v[220:223], v[74:77]
	v_mfma_f32_16x16x32_bf16 v[74:77], v[184:187], v[224:227], v[74:77]
	v_mfma_f32_16x16x32_bf16 v[114:117], v[188:191], v[196:199], v[114:117]
	v_mfma_f32_16x16x32_bf16 v[114:117], v[192:195], v[200:203], v[114:117]
	v_mfma_f32_16x16x32_bf16 v[98:101], v[188:191], v[204:207], v[98:101]
	v_mfma_f32_16x16x32_bf16 v[98:101], v[192:195], v[208:211], v[98:101]
	v_mfma_f32_16x16x32_bf16 v[82:85], v[188:191], v[212:215], v[82:85]
	v_mfma_f32_16x16x32_bf16 v[82:85], v[192:195], v[216:219], v[82:85]
	v_mfma_f32_16x16x32_bf16 v[66:69], v[188:191], v[220:223], v[66:69]
	v_mfma_f32_16x16x32_bf16 v[66:69], v[192:195], v[224:227], v[66:69]
	s_setprio 0
	s_barrier
	s_add_i32 s83, s68, s13
	s_add_u32 s98, s40, 0x80
	s_addc_u32 s99, s41, 0
	s_mov_b32 m0, s83
	ds_read_b128 v[196:199], v161 offset:16384
	ds_read_b128 v[200:203], v161 offset:17408
	ds_read_b128 v[204:207], v161 offset:18432
	ds_read_b128 v[208:211], v161 offset:19456
	ds_read_b128 v[212:215], v161 offset:20480
	ds_read_b128 v[216:219], v161 offset:21504
	ds_read_b128 v[220:223], v161 offset:22528
	ds_read_b128 v[224:227], v161 offset:23552
	global_load_lds_dwordx4 v132, s[40:41]
	s_add_i32 m0, s83, 0x2000
	s_add_u32 s84, s40, 0x100000
	s_addc_u32 s85, s41, 0
	s_add_i32 s83, s69, s13
	global_load_lds_dwordx4 v136, s[40:41]
	s_mov_b32 m0, s83
	global_load_lds_dwordx4 v132, s[84:85]
	s_add_i32 m0, s83, 0x2000
	s_nop 0
	global_load_lds_dwordx4 v136, s[84:85]
	s_add_u32 s100, s42, 0x80
	s_addc_u32 s101, s43, 0
	s_mov_b32 m0, s44
	s_nop 0
	global_load_lds_dwordx4 v130, s[42:43]
	s_mov_b32 m0, s45
	s_nop 0
	global_load_lds_dwordx4 v134, s[42:43]
	s_waitcnt vmcnt(8)
	s_waitcnt lgkmcnt(0)
	s_barrier
	s_setprio 1
	v_mfma_f32_16x16x32_bf16 v[62:65], v[148:151], v[196:199], v[62:65]
	v_mfma_f32_16x16x32_bf16 v[62:65], v[164:167], v[200:203], v[62:65]
	v_mfma_f32_16x16x32_bf16 v[46:49], v[148:151], v[204:207], v[46:49]
	v_mfma_f32_16x16x32_bf16 v[46:49], v[164:167], v[208:211], v[46:49]
	v_mfma_f32_16x16x32_bf16 v[30:33], v[148:151], v[212:215], v[30:33]
	v_mfma_f32_16x16x32_bf16 v[30:33], v[164:167], v[216:219], v[30:33]
	v_mfma_f32_16x16x32_bf16 v[14:17], v[148:151], v[220:223], v[14:17]
	v_mfma_f32_16x16x32_bf16 v[14:17], v[164:167], v[224:227], v[14:17]
	v_mfma_f32_16x16x32_bf16 v[54:57], v[168:171], v[196:199], v[54:57]
	v_mfma_f32_16x16x32_bf16 v[54:57], v[172:175], v[200:203], v[54:57]
	v_mfma_f32_16x16x32_bf16 v[38:41], v[168:171], v[204:207], v[38:41]
	v_mfma_f32_16x16x32_bf16 v[38:41], v[172:175], v[208:211], v[38:41]
	v_mfma_f32_16x16x32_bf16 v[22:25], v[168:171], v[212:215], v[22:25]
	v_mfma_f32_16x16x32_bf16 v[22:25], v[172:175], v[216:219], v[22:25]
	v_mfma_f32_16x16x32_bf16 v[6:9], v[168:171], v[220:223], v[6:9]
	v_mfma_f32_16x16x32_bf16 v[6:9], v[172:175], v[224:227], v[6:9]
	v_mfma_f32_16x16x32_bf16 v[58:61], v[176:179], v[196:199], v[58:61]
	v_mfma_f32_16x16x32_bf16 v[58:61], v[184:187], v[200:203], v[58:61]
	v_mfma_f32_16x16x32_bf16 v[42:45], v[176:179], v[204:207], v[42:45]
	v_mfma_f32_16x16x32_bf16 v[42:45], v[184:187], v[208:211], v[42:45]
	v_mfma_f32_16x16x32_bf16 v[26:29], v[176:179], v[212:215], v[26:29]
	v_mfma_f32_16x16x32_bf16 v[26:29], v[184:187], v[216:219], v[26:29]
	v_mfma_f32_16x16x32_bf16 v[10:13], v[176:179], v[220:223], v[10:13]
	v_mfma_f32_16x16x32_bf16 v[10:13], v[184:187], v[224:227], v[10:13]
	v_mfma_f32_16x16x32_bf16 v[50:53], v[188:191], v[196:199], v[50:53]
	v_mfma_f32_16x16x32_bf16 v[50:53], v[192:195], v[200:203], v[50:53]
	v_mfma_f32_16x16x32_bf16 v[34:37], v[188:191], v[204:207], v[34:37]
	v_mfma_f32_16x16x32_bf16 v[34:37], v[192:195], v[208:211], v[34:37]
	v_mfma_f32_16x16x32_bf16 v[18:21], v[188:191], v[212:215], v[18:21]
	v_mfma_f32_16x16x32_bf16 v[18:21], v[192:195], v[216:219], v[18:21]
	v_mfma_f32_16x16x32_bf16 v[2:5], v[188:191], v[220:223], v[2:5]
	v_mfma_f32_16x16x32_bf16 v[2:5], v[192:195], v[224:227], v[2:5]
	s_setprio 0
	s_barrier
	s_add_i32 s83, 0, 0x18000
	v_add_u32_e32 v138, s83, v155
	s_add_i32 s84, 0, 0x1c000
	ds_read_b128 v[148:151], v138
	ds_read_b128 v[164:167], v138 offset:1024
	ds_read_b128 v[168:171], v138 offset:2048
	ds_read_b128 v[172:175], v138 offset:3072
	v_add_u32_e32 v138, s84, v155
	ds_read_b128 v[176:179], v138
	ds_read_b128 v[184:187], v138 offset:1024
	ds_read_b128 v[188:191], v138 offset:2048
	ds_read_b128 v[192:195], v138 offset:3072
	s_add_u32 s42, s42, 0x100000
	s_addc_u32 s43, s43, 0
	s_mov_b32 m0, s46
	ds_read_b128 v[196:199], v161 offset:32768
	ds_read_b128 v[200:203], v161 offset:33792
	ds_read_b128 v[204:207], v161 offset:34816
	ds_read_b128 v[208:211], v161 offset:35840
	ds_read_b128 v[212:215], v161 offset:36864
	ds_read_b128 v[216:219], v161 offset:37888
	ds_read_b128 v[220:223], v161 offset:38912
	ds_read_b128 v[224:227], v161 offset:39936
	global_load_lds_dwordx4 v130, s[42:43]
	s_mov_b32 m0, s47
	s_nop 0
	global_load_lds_dwordx4 v134, s[42:43]
	s_waitcnt vmcnt(8)
	s_waitcnt lgkmcnt(0)
	s_barrier
	s_setprio 1
	v_mfma_f32_16x16x32_bf16 v[126:129], v[148:151], v[196:199], v[126:129]
	v_mfma_f32_16x16x32_bf16 v[126:129], v[164:167], v[200:203], v[126:129]
	v_mfma_f32_16x16x32_bf16 v[110:113], v[148:151], v[204:207], v[110:113]
	v_mfma_f32_16x16x32_bf16 v[110:113], v[164:167], v[208:211], v[110:113]
	v_mfma_f32_16x16x32_bf16 v[94:97], v[148:151], v[212:215], v[94:97]
	v_mfma_f32_16x16x32_bf16 v[94:97], v[164:167], v[216:219], v[94:97]
	v_mfma_f32_16x16x32_bf16 v[78:81], v[148:151], v[220:223], v[78:81]
	v_mfma_f32_16x16x32_bf16 v[78:81], v[164:167], v[224:227], v[78:81]
	v_mfma_f32_16x16x32_bf16 v[118:121], v[168:171], v[196:199], v[118:121]
	v_mfma_f32_16x16x32_bf16 v[118:121], v[172:175], v[200:203], v[118:121]
	v_mfma_f32_16x16x32_bf16 v[102:105], v[168:171], v[204:207], v[102:105]
	v_mfma_f32_16x16x32_bf16 v[102:105], v[172:175], v[208:211], v[102:105]
	v_mfma_f32_16x16x32_bf16 v[86:89], v[168:171], v[212:215], v[86:89]
	v_mfma_f32_16x16x32_bf16 v[86:89], v[172:175], v[216:219], v[86:89]
	v_mfma_f32_16x16x32_bf16 v[70:73], v[168:171], v[220:223], v[70:73]
	v_mfma_f32_16x16x32_bf16 v[70:73], v[172:175], v[224:227], v[70:73]
	v_mfma_f32_16x16x32_bf16 v[122:125], v[176:179], v[196:199], v[122:125]
	v_mfma_f32_16x16x32_bf16 v[122:125], v[184:187], v[200:203], v[122:125]
	v_mfma_f32_16x16x32_bf16 v[106:109], v[176:179], v[204:207], v[106:109]
	v_mfma_f32_16x16x32_bf16 v[106:109], v[184:187], v[208:211], v[106:109]
	v_mfma_f32_16x16x32_bf16 v[90:93], v[176:179], v[212:215], v[90:93]
	v_mfma_f32_16x16x32_bf16 v[90:93], v[184:187], v[216:219], v[90:93]
	v_mfma_f32_16x16x32_bf16 v[74:77], v[176:179], v[220:223], v[74:77]
	v_mfma_f32_16x16x32_bf16 v[74:77], v[184:187], v[224:227], v[74:77]
	v_mfma_f32_16x16x32_bf16 v[114:117], v[188:191], v[196:199], v[114:117]
	v_mfma_f32_16x16x32_bf16 v[114:117], v[192:195], v[200:203], v[114:117]
	v_mfma_f32_16x16x32_bf16 v[98:101], v[188:191], v[204:207], v[98:101]
	v_mfma_f32_16x16x32_bf16 v[98:101], v[192:195], v[208:211], v[98:101]
	v_mfma_f32_16x16x32_bf16 v[82:85], v[188:191], v[212:215], v[82:85]
	v_mfma_f32_16x16x32_bf16 v[82:85], v[192:195], v[216:219], v[82:85]
	v_mfma_f32_16x16x32_bf16 v[66:69], v[188:191], v[220:223], v[66:69]
	v_mfma_f32_16x16x32_bf16 v[66:69], v[192:195], v[224:227], v[66:69]
	s_setprio 0
	s_barrier
	s_add_i32 s42, s83, s13
	s_mov_b32 m0, s42
	ds_read_b128 v[196:199], v161 offset:49152
	ds_read_b128 v[200:203], v161 offset:50176
	ds_read_b128 v[204:207], v161 offset:51200
	ds_read_b128 v[208:211], v161 offset:52224
	ds_read_b128 v[212:215], v161 offset:53248
	ds_read_b128 v[216:219], v161 offset:54272
	ds_read_b128 v[220:223], v161 offset:55296
	ds_read_b128 v[224:227], v161 offset:56320
	global_load_lds_dwordx4 v132, s[98:99]
	s_add_i32 m0, s42, 0x2000
	s_add_u32 s40, s40, 0x100080
	s_addc_u32 s41, s41, 0
	s_add_i32 s42, s84, s13
	global_load_lds_dwordx4 v136, s[98:99]
	s_mov_b32 m0, s42
	s_nop 0
	global_load_lds_dwordx4 v132, s[40:41]
	s_add_i32 m0, s42, 0x2000
	s_nop 0
	global_load_lds_dwordx4 v136, s[40:41]
	s_mov_b32 m0, s59
	s_nop 0
	global_load_lds_dwordx4 v130, s[100:101]
	s_mov_b32 m0, s62
	s_nop 0
	global_load_lds_dwordx4 v134, s[100:101]
	s_waitcnt vmcnt(8)
	s_waitcnt lgkmcnt(0)
	s_barrier
	s_setprio 1
	v_mfma_f32_16x16x32_bf16 v[62:65], v[148:151], v[196:199], v[62:65]
	v_mfma_f32_16x16x32_bf16 v[62:65], v[164:167], v[200:203], v[62:65]
	v_mfma_f32_16x16x32_bf16 v[46:49], v[148:151], v[204:207], v[46:49]
	v_mfma_f32_16x16x32_bf16 v[46:49], v[164:167], v[208:211], v[46:49]
	v_mfma_f32_16x16x32_bf16 v[30:33], v[148:151], v[212:215], v[30:33]
	v_mfma_f32_16x16x32_bf16 v[30:33], v[164:167], v[216:219], v[30:33]
	v_mfma_f32_16x16x32_bf16 v[14:17], v[148:151], v[220:223], v[14:17]
	v_mfma_f32_16x16x32_bf16 v[14:17], v[164:167], v[224:227], v[14:17]
	v_mfma_f32_16x16x32_bf16 v[54:57], v[168:171], v[196:199], v[54:57]
	v_mfma_f32_16x16x32_bf16 v[54:57], v[172:175], v[200:203], v[54:57]
	v_mfma_f32_16x16x32_bf16 v[38:41], v[168:171], v[204:207], v[38:41]
	v_mfma_f32_16x16x32_bf16 v[38:41], v[172:175], v[208:211], v[38:41]
	v_mfma_f32_16x16x32_bf16 v[22:25], v[168:171], v[212:215], v[22:25]
	v_mfma_f32_16x16x32_bf16 v[22:25], v[172:175], v[216:219], v[22:25]
	v_mfma_f32_16x16x32_bf16 v[6:9], v[168:171], v[220:223], v[6:9]
	v_mfma_f32_16x16x32_bf16 v[6:9], v[172:175], v[224:227], v[6:9]
	v_mfma_f32_16x16x32_bf16 v[58:61], v[176:179], v[196:199], v[58:61]
	v_mfma_f32_16x16x32_bf16 v[58:61], v[184:187], v[200:203], v[58:61]
	v_mfma_f32_16x16x32_bf16 v[42:45], v[176:179], v[204:207], v[42:45]
	v_mfma_f32_16x16x32_bf16 v[42:45], v[184:187], v[208:211], v[42:45]
	v_mfma_f32_16x16x32_bf16 v[26:29], v[176:179], v[212:215], v[26:29]
	v_mfma_f32_16x16x32_bf16 v[26:29], v[184:187], v[216:219], v[26:29]
	v_mfma_f32_16x16x32_bf16 v[10:13], v[176:179], v[220:223], v[10:13]
	v_mfma_f32_16x16x32_bf16 v[10:13], v[184:187], v[224:227], v[10:13]
	v_mfma_f32_16x16x32_bf16 v[50:53], v[188:191], v[196:199], v[50:53]
	v_mfma_f32_16x16x32_bf16 v[50:53], v[192:195], v[200:203], v[50:53]
	v_mfma_f32_16x16x32_bf16 v[34:37], v[188:191], v[204:207], v[34:37]
	v_mfma_f32_16x16x32_bf16 v[34:37], v[192:195], v[208:211], v[34:37]
	v_mfma_f32_16x16x32_bf16 v[18:21], v[188:191], v[212:215], v[18:21]
	v_mfma_f32_16x16x32_bf16 v[18:21], v[192:195], v[216:219], v[18:21]
	v_mfma_f32_16x16x32_bf16 v[2:5], v[188:191], v[220:223], v[2:5]
	v_mfma_f32_16x16x32_bf16 v[2:5], v[192:195], v[224:227], v[2:5]
	s_setprio 0
	s_barrier
	s_add_i32 s82, s82, 2
	s_add_u32 s6, s6, 0x100
	s_addc_u32 s7, s7, 0
	s_add_u32 s80, s80, 0x100
	s_addc_u32 s81, s81, 0
	s_cmp_gt_u32 s82, 61
	s_cbranch_scc0 .LBB0_2720
	s_and_b64 vcc, exec, s[24:25]
	s_cbranch_vccz .LBB0_2723
	s_barrier

.LBB0_2805:
	ds_read_b128 v[130:133], v163
	ds_read_b128 v[134:137], v163 offset:1024
	ds_read_b128 v[138:141], v163 offset:2048
	ds_read_b128 v[142:145], v163 offset:3072
	ds_read_b128 v[146:149], v188
	ds_read_b128 v[150:153], v188 offset:1024
	ds_read_b128 v[174:177], v188 offset:2048
	ds_read_b128 v[178:181], v188 offset:3072
	s_add_u32 s28, s26, 0xffd50080
	s_addc_u32 s29, s27, -1
	s_cmpk_eq_i32 s62, 0xa8
	s_cselect_b32 s37, s7, s29
	s_cselect_b32 s36, s6, s28
	s_cselect_b32 s29, s25, s59
	s_cselect_b32 s28, s24, s12
	s_add_i32 m0, s38, 0xc000
	ds_read_b128 v[184:187], v189
	ds_read_b128 v[192:195], v189 offset:1024
	ds_read_b128 v[196:199], v189 offset:2048
	ds_read_b128 v[200:203], v189 offset:3072
	ds_read_b128 v[204:207], v189 offset:4096
	ds_read_b128 v[208:211], v189 offset:5120
	ds_read_b128 v[212:215], v189 offset:6144
	ds_read_b128 v[216:219], v189 offset:7168
	global_load_lds_dwordx4 v166, s[26:27]
	s_add_i32 m0, s38, 0xe000
	s_nop 0
	global_load_lds_dwordx4 v168, s[26:27]
	s_waitcnt vmcnt(8)
	s_waitcnt lgkmcnt(0)
	s_barrier
	s_setprio 1
	v_mfma_f32_16x16x32_bf16 v[126:129], v[130:133], v[184:187], v[126:129]
	v_mfma_f32_16x16x32_bf16 v[126:129], v[134:137], v[192:195], v[126:129]
	v_mfma_f32_16x16x32_bf16 v[110:113], v[130:133], v[196:199], v[110:113]
	v_mfma_f32_16x16x32_bf16 v[110:113], v[134:137], v[200:203], v[110:113]
	v_mfma_f32_16x16x32_bf16 v[94:97], v[130:133], v[204:207], v[94:97]
	v_mfma_f32_16x16x32_bf16 v[94:97], v[134:137], v[208:211], v[94:97]
	v_mfma_f32_16x16x32_bf16 v[78:81], v[130:133], v[212:215], v[78:81]
	v_mfma_f32_16x16x32_bf16 v[78:81], v[134:137], v[216:219], v[78:81]
	v_mfma_f32_16x16x32_bf16 v[122:125], v[138:141], v[184:187], v[122:125]
	v_mfma_f32_16x16x32_bf16 v[122:125], v[142:145], v[192:195], v[122:125]
	v_mfma_f32_16x16x32_bf16 v[106:109], v[138:141], v[196:199], v[106:109]
	v_mfma_f32_16x16x32_bf16 v[106:109], v[142:145], v[200:203], v[106:109]
	v_mfma_f32_16x16x32_bf16 v[90:93], v[138:141], v[204:207], v[90:93]
	v_mfma_f32_16x16x32_bf16 v[90:93], v[142:145], v[208:211], v[90:93]
	v_mfma_f32_16x16x32_bf16 v[74:77], v[138:141], v[212:215], v[74:77]
	v_mfma_f32_16x16x32_bf16 v[74:77], v[142:145], v[216:219], v[74:77]
	v_mfma_f32_16x16x32_bf16 v[118:121], v[146:149], v[184:187], v[118:121]
	v_mfma_f32_16x16x32_bf16 v[118:121], v[150:153], v[192:195], v[118:121]
	v_mfma_f32_16x16x32_bf16 v[102:105], v[146:149], v[196:199], v[102:105]
	v_mfma_f32_16x16x32_bf16 v[102:105], v[150:153], v[200:203], v[102:105]
	v_mfma_f32_16x16x32_bf16 v[86:89], v[146:149], v[204:207], v[86:89]
	v_mfma_f32_16x16x32_bf16 v[86:89], v[150:153], v[208:211], v[86:89]
	v_mfma_f32_16x16x32_bf16 v[70:73], v[146:149], v[212:215], v[70:73]
	v_mfma_f32_16x16x32_bf16 v[70:73], v[150:153], v[216:219], v[70:73]
	v_mfma_f32_16x16x32_bf16 v[114:117], v[174:177], v[184:187], v[114:117]
	v_mfma_f32_16x16x32_bf16 v[114:117], v[178:181], v[192:195], v[114:117]
	v_mfma_f32_16x16x32_bf16 v[98:101], v[174:177], v[196:199], v[98:101]
	v_mfma_f32_16x16x32_bf16 v[98:101], v[178:181], v[200:203], v[98:101]
	v_mfma_f32_16x16x32_bf16 v[82:85], v[174:177], v[204:207], v[82:85]
	v_mfma_f32_16x16x32_bf16 v[82:85], v[178:181], v[208:211], v[82:85]
	v_mfma_f32_16x16x32_bf16 v[66:69], v[174:177], v[212:215], v[66:69]
	v_mfma_f32_16x16x32_bf16 v[66:69], v[178:181], v[216:219], v[66:69]
	s_setprio 0
	s_barrier
	s_add_i32 s63, s47, s35
	s_add_u32 s98, s28, 0x80
	s_addc_u32 s99, s29, 0
	s_mov_b32 m0, s63
	ds_read_b128 v[184:187], v189 offset:16384
	ds_read_b128 v[192:195], v189 offset:17408
	ds_read_b128 v[196:199], v189 offset:18432
	ds_read_b128 v[200:203], v189 offset:19456
	ds_read_b128 v[204:207], v189 offset:20480
	ds_read_b128 v[208:211], v189 offset:21504
	ds_read_b128 v[212:215], v189 offset:22528
	ds_read_b128 v[216:219], v189 offset:23552
	global_load_lds_dwordx4 v156, s[28:29]
	s_add_i32 m0, s63, 0x2000
	s_add_u32 s66, s28, 0x2b0000
	s_addc_u32 s67, s29, 0
	s_add_i32 s63, s48, s35
	global_load_lds_dwordx4 v160, s[28:29]
	s_mov_b32 m0, s63
	global_load_lds_dwordx4 v156, s[66:67]
	s_add_i32 m0, s63, 0x2000
	s_nop 0
	global_load_lds_dwordx4 v160, s[66:67]
	s_add_u32 s100, s36, 0x80
	s_addc_u32 s101, s37, 0
	s_mov_b32 m0, s38
	s_nop 0
	global_load_lds_dwordx4 v154, s[36:37]
	s_mov_b32 m0, s39
	s_nop 0
	global_load_lds_dwordx4 v158, s[36:37]
	s_waitcnt vmcnt(8)
	s_waitcnt lgkmcnt(0)
	s_barrier
	s_setprio 1
	v_mfma_f32_16x16x32_bf16 v[62:65], v[130:133], v[184:187], v[62:65]
	v_mfma_f32_16x16x32_bf16 v[62:65], v[134:137], v[192:195], v[62:65]
	v_mfma_f32_16x16x32_bf16 v[46:49], v[130:133], v[196:199], v[46:49]
	v_mfma_f32_16x16x32_bf16 v[46:49], v[134:137], v[200:203], v[46:49]
	v_mfma_f32_16x16x32_bf16 v[30:33], v[130:133], v[204:207], v[30:33]
	v_mfma_f32_16x16x32_bf16 v[30:33], v[134:137], v[208:211], v[30:33]
	v_mfma_f32_16x16x32_bf16 v[14:17], v[130:133], v[212:215], v[14:17]
	v_mfma_f32_16x16x32_bf16 v[14:17], v[134:137], v[216:219], v[14:17]
	v_mfma_f32_16x16x32_bf16 v[58:61], v[138:141], v[184:187], v[58:61]
	v_mfma_f32_16x16x32_bf16 v[58:61], v[142:145], v[192:195], v[58:61]
	v_mfma_f32_16x16x32_bf16 v[42:45], v[138:141], v[196:199], v[42:45]
	v_mfma_f32_16x16x32_bf16 v[42:45], v[142:145], v[200:203], v[42:45]
	v_mfma_f32_16x16x32_bf16 v[26:29], v[138:141], v[204:207], v[26:29]
	v_mfma_f32_16x16x32_bf16 v[26:29], v[142:145], v[208:211], v[26:29]
	v_mfma_f32_16x16x32_bf16 v[10:13], v[138:141], v[212:215], v[10:13]
	v_mfma_f32_16x16x32_bf16 v[10:13], v[142:145], v[216:219], v[10:13]
	v_mfma_f32_16x16x32_bf16 v[54:57], v[146:149], v[184:187], v[54:57]
	v_mfma_f32_16x16x32_bf16 v[54:57], v[150:153], v[192:195], v[54:57]
	v_mfma_f32_16x16x32_bf16 v[38:41], v[146:149], v[196:199], v[38:41]
	v_mfma_f32_16x16x32_bf16 v[38:41], v[150:153], v[200:203], v[38:41]
	v_mfma_f32_16x16x32_bf16 v[22:25], v[146:149], v[204:207], v[22:25]
	v_mfma_f32_16x16x32_bf16 v[22:25], v[150:153], v[208:211], v[22:25]
	v_mfma_f32_16x16x32_bf16 v[6:9], v[146:149], v[212:215], v[6:9]
	v_mfma_f32_16x16x32_bf16 v[6:9], v[150:153], v[216:219], v[6:9]
	v_mfma_f32_16x16x32_bf16 v[50:53], v[174:177], v[184:187], v[50:53]
	v_mfma_f32_16x16x32_bf16 v[50:53], v[178:181], v[192:195], v[50:53]
	v_mfma_f32_16x16x32_bf16 v[34:37], v[174:177], v[196:199], v[34:37]
	v_mfma_f32_16x16x32_bf16 v[34:37], v[178:181], v[200:203], v[34:37]
	v_mfma_f32_16x16x32_bf16 v[18:21], v[174:177], v[204:207], v[18:21]
	v_mfma_f32_16x16x32_bf16 v[18:21], v[178:181], v[208:211], v[18:21]
	v_mfma_f32_16x16x32_bf16 v[2:5], v[174:177], v[212:215], v[2:5]
	v_mfma_f32_16x16x32_bf16 v[2:5], v[178:181], v[216:219], v[2:5]
	s_setprio 0
	s_barrier
	s_add_i32 s63, 0, 0x18000
	s_add_i32 s65, 0, 0x1c000
	v_add_u32_e32 v142, s63, v1
	v_add_u32_e32 v178, s65, v1
	ds_read_b128 v[130:133], v142
	ds_read_b128 v[134:137], v142 offset:1024
	ds_read_b128 v[138:141], v142 offset:2048
	ds_read_b128 v[142:145], v142 offset:3072
	ds_read_b128 v[146:149], v178
	ds_read_b128 v[150:153], v178 offset:1024
	ds_read_b128 v[174:177], v178 offset:2048
	ds_read_b128 v[178:181], v178 offset:3072
	s_add_u32 s36, s36, 0x2b0000
	s_addc_u32 s37, s37, 0
	s_mov_b32 m0, s40
	ds_read_b128 v[184:187], v189 offset:32768
	ds_read_b128 v[192:195], v189 offset:33792
	ds_read_b128 v[196:199], v189 offset:34816
	ds_read_b128 v[200:203], v189 offset:35840
	ds_read_b128 v[204:207], v189 offset:36864
	ds_read_b128 v[208:211], v189 offset:37888
	ds_read_b128 v[212:215], v189 offset:38912
	ds_read_b128 v[216:219], v189 offset:39936
	global_load_lds_dwordx4 v154, s[36:37]
	s_mov_b32 m0, s41
	s_nop 0
	global_load_lds_dwordx4 v158, s[36:37]
	s_waitcnt vmcnt(8)
	s_waitcnt lgkmcnt(0)
	s_barrier
	s_setprio 1
	v_mfma_f32_16x16x32_bf16 v[126:129], v[130:133], v[184:187], v[126:129]
	v_mfma_f32_16x16x32_bf16 v[126:129], v[134:137], v[192:195], v[126:129]
	v_mfma_f32_16x16x32_bf16 v[110:113], v[130:133], v[196:199], v[110:113]
	v_mfma_f32_16x16x32_bf16 v[110:113], v[134:137], v[200:203], v[110:113]
	v_mfma_f32_16x16x32_bf16 v[94:97], v[130:133], v[204:207], v[94:97]
	v_mfma_f32_16x16x32_bf16 v[94:97], v[134:137], v[208:211], v[94:97]
	v_mfma_f32_16x16x32_bf16 v[78:81], v[130:133], v[212:215], v[78:81]
	v_mfma_f32_16x16x32_bf16 v[78:81], v[134:137], v[216:219], v[78:81]
	v_mfma_f32_16x16x32_bf16 v[122:125], v[138:141], v[184:187], v[122:125]
	v_mfma_f32_16x16x32_bf16 v[122:125], v[142:145], v[192:195], v[122:125]
	v_mfma_f32_16x16x32_bf16 v[106:109], v[138:141], v[196:199], v[106:109]
	v_mfma_f32_16x16x32_bf16 v[106:109], v[142:145], v[200:203], v[106:109]
	v_mfma_f32_16x16x32_bf16 v[90:93], v[138:141], v[204:207], v[90:93]
	v_mfma_f32_16x16x32_bf16 v[90:93], v[142:145], v[208:211], v[90:93]
	v_mfma_f32_16x16x32_bf16 v[74:77], v[138:141], v[212:215], v[74:77]
	v_mfma_f32_16x16x32_bf16 v[74:77], v[142:145], v[216:219], v[74:77]
	v_mfma_f32_16x16x32_bf16 v[118:121], v[146:149], v[184:187], v[118:121]
	v_mfma_f32_16x16x32_bf16 v[118:121], v[150:153], v[192:195], v[118:121]
	v_mfma_f32_16x16x32_bf16 v[102:105], v[146:149], v[196:199], v[102:105]
	v_mfma_f32_16x16x32_bf16 v[102:105], v[150:153], v[200:203], v[102:105]
	v_mfma_f32_16x16x32_bf16 v[86:89], v[146:149], v[204:207], v[86:89]
	v_mfma_f32_16x16x32_bf16 v[86:89], v[150:153], v[208:211], v[86:89]
	v_mfma_f32_16x16x32_bf16 v[70:73], v[146:149], v[212:215], v[70:73]
	v_mfma_f32_16x16x32_bf16 v[70:73], v[150:153], v[216:219], v[70:73]
	v_mfma_f32_16x16x32_bf16 v[114:117], v[174:177], v[184:187], v[114:117]
	v_mfma_f32_16x16x32_bf16 v[114:117], v[178:181], v[192:195], v[114:117]
	v_mfma_f32_16x16x32_bf16 v[98:101], v[174:177], v[196:199], v[98:101]
	v_mfma_f32_16x16x32_bf16 v[98:101], v[178:181], v[200:203], v[98:101]
	v_mfma_f32_16x16x32_bf16 v[82:85], v[174:177], v[204:207], v[82:85]
	v_mfma_f32_16x16x32_bf16 v[82:85], v[178:181], v[208:211], v[82:85]
	v_mfma_f32_16x16x32_bf16 v[66:69], v[174:177], v[212:215], v[66:69]
	v_mfma_f32_16x16x32_bf16 v[66:69], v[178:181], v[216:219], v[66:69]
	s_setprio 0
	s_barrier
	s_add_i32 s36, s63, s35
	s_mov_b32 m0, s36
	ds_read_b128 v[184:187], v189 offset:49152
	ds_read_b128 v[192:195], v189 offset:50176
	ds_read_b128 v[196:199], v189 offset:51200
	ds_read_b128 v[200:203], v189 offset:52224
	ds_read_b128 v[204:207], v189 offset:53248
	ds_read_b128 v[208:211], v189 offset:54272
	ds_read_b128 v[212:215], v189 offset:55296
	ds_read_b128 v[216:219], v189 offset:56320
	global_load_lds_dwordx4 v156, s[98:99]
	s_add_i32 m0, s36, 0x2000
	s_add_u32 s28, s28, 0x2b0080
	s_addc_u32 s29, s29, 0
	s_add_i32 s36, s65, s35
	global_load_lds_dwordx4 v160, s[98:99]
	s_mov_b32 m0, s36
	s_nop 0
	global_load_lds_dwordx4 v156, s[28:29]
	s_add_i32 m0, s36, 0x2000
	s_nop 0
	global_load_lds_dwordx4 v160, s[28:29]
	s_mov_b32 m0, s43
	s_nop 0
	global_load_lds_dwordx4 v154, s[100:101]
	s_mov_b32 m0, s44
	s_nop 0
	global_load_lds_dwordx4 v158, s[100:101]
	s_waitcnt vmcnt(8)
	s_waitcnt lgkmcnt(0)
	s_barrier
	s_setprio 1
	v_mfma_f32_16x16x32_bf16 v[62:65], v[130:133], v[184:187], v[62:65]
	v_mfma_f32_16x16x32_bf16 v[62:65], v[134:137], v[192:195], v[62:65]
	v_mfma_f32_16x16x32_bf16 v[46:49], v[130:133], v[196:199], v[46:49]
	v_mfma_f32_16x16x32_bf16 v[46:49], v[134:137], v[200:203], v[46:49]
	v_mfma_f32_16x16x32_bf16 v[30:33], v[130:133], v[204:207], v[30:33]
	v_mfma_f32_16x16x32_bf16 v[30:33], v[134:137], v[208:211], v[30:33]
	v_mfma_f32_16x16x32_bf16 v[14:17], v[130:133], v[212:215], v[14:17]
	v_mfma_f32_16x16x32_bf16 v[14:17], v[134:137], v[216:219], v[14:17]
	v_mfma_f32_16x16x32_bf16 v[58:61], v[138:141], v[184:187], v[58:61]
	v_mfma_f32_16x16x32_bf16 v[58:61], v[142:145], v[192:195], v[58:61]
	v_mfma_f32_16x16x32_bf16 v[42:45], v[138:141], v[196:199], v[42:45]
	v_mfma_f32_16x16x32_bf16 v[42:45], v[142:145], v[200:203], v[42:45]
	v_mfma_f32_16x16x32_bf16 v[26:29], v[138:141], v[204:207], v[26:29]
	v_mfma_f32_16x16x32_bf16 v[26:29], v[142:145], v[208:211], v[26:29]
	v_mfma_f32_16x16x32_bf16 v[10:13], v[138:141], v[212:215], v[10:13]
	v_mfma_f32_16x16x32_bf16 v[10:13], v[142:145], v[216:219], v[10:13]
	v_mfma_f32_16x16x32_bf16 v[54:57], v[146:149], v[184:187], v[54:57]
	v_mfma_f32_16x16x32_bf16 v[54:57], v[150:153], v[192:195], v[54:57]
	v_mfma_f32_16x16x32_bf16 v[38:41], v[146:149], v[196:199], v[38:41]
	v_mfma_f32_16x16x32_bf16 v[38:41], v[150:153], v[200:203], v[38:41]
	v_mfma_f32_16x16x32_bf16 v[22:25], v[146:149], v[204:207], v[22:25]
	v_mfma_f32_16x16x32_bf16 v[22:25], v[150:153], v[208:211], v[22:25]
	v_mfma_f32_16x16x32_bf16 v[6:9], v[146:149], v[212:215], v[6:9]
	v_mfma_f32_16x16x32_bf16 v[6:9], v[150:153], v[216:219], v[6:9]
	v_mfma_f32_16x16x32_bf16 v[50:53], v[174:177], v[184:187], v[50:53]
	v_mfma_f32_16x16x32_bf16 v[50:53], v[178:181], v[192:195], v[50:53]
	v_mfma_f32_16x16x32_bf16 v[34:37], v[174:177], v[196:199], v[34:37]
	v_mfma_f32_16x16x32_bf16 v[34:37], v[178:181], v[200:203], v[34:37]
	v_mfma_f32_16x16x32_bf16 v[18:21], v[174:177], v[204:207], v[18:21]
	v_mfma_f32_16x16x32_bf16 v[18:21], v[178:181], v[208:211], v[18:21]
	v_mfma_f32_16x16x32_bf16 v[2:5], v[174:177], v[212:215], v[2:5]
	v_mfma_f32_16x16x32_bf16 v[2:5], v[178:181], v[216:219], v[2:5]
	s_setprio 0
	s_barrier
	s_add_i32 s62, s62, 2
	s_add_u32 s26, s26, 0x100
	s_addc_u32 s27, s27, 0
	s_add_u32 s12, s12, 0x100
	s_addc_u32 s59, s59, 0
	s_cmpk_gt_u32 s62, 0xa9
	s_cbranch_scc0 .LBB0_2805
	s_and_b64 vcc, exec, s[22:23]
	s_cbranch_vccz .LBB0_2808
	s_barrier
